# v52 plus saddr-form LDS-DMA in the P7/P9 main loops (30 fewer 64-bit VALU per iteration) and 64-bit accumulator clears
# speedup vs baseline: 1.0039x; 1.0017x over previous
; template <class Epi, class Sched, bool ALIGN_EPI = false, bool SP2 = false>
; __device__ __forceinline__ void gemm_phase(PG8_LAS unsigned char* lds, const Gemm g, const Sched& S, const Epi& E) {
;     ...
;         const char* nA = has_next ? (const char*)g.A + (size_t)nxt.pm * tstep : cA; const char* nB = has_next ? (const char*)g.Bt + (size_t)nxt.pn * tstep : cB;
;         for (int t = 0; t < nt; t += 2) {
;             const bool last = (t == nt - 2);
;             const char* a1 = cA + (size_t)(t + 1) * kstep;
;             const char* a2 = last ? nA : cA + (size_t)(t + 2) * kstep; const char* b2 = last ? nB : cB + (size_t)(t + 2) * kstep;
;     ...
;         for (int a = 0; a < 2; ++a)
; #pragma unroll
;             for (int b = 0; b < 2; ++b)
; #pragma unroll
;                 for (int m = 0; m < 4; ++m)
; #pragma unroll
;                     for (int n = 0; n < 2; ++n) acc[a][b][m][n] = (f32x4){0.f, 0.f, 0.f, 0.f};
.LBB0_138:
	s_ashr_i32 s79, s78, 31
	s_lshl_b64 s[16:17], s[78:79], 21
	s_add_u32 s82, s36, s16
	s_addc_u32 s83, s37, s17
	s_and_b64 s[16:17], s[8:9], exec
	s_cselect_b32 s2, s83, s13
	s_cselect_b32 s11, s82, s12
	s_ashr_i32 s81, s80, 31
	s_lshl_b64 s[16:17], s[80:81], 21
	s_add_u32 s84, s42, s16
	s_addc_u32 s85, s43, s17
	s_and_b64 s[16:17], s[8:9], exec
	s_cselect_b32 s26, s85, s15
	s_cselect_b32 s28, s84, s14
	s_add_u32 s12, s12, 0x100080
	s_addc_u32 s13, s13, 0
	s_add_u32 s29, s14, 0x100
	v_mov_b32_e32 v10, 0
	s_addc_u32 s30, s15, 0
	s_mov_b32 s33, -2
	v_mov_b64_e32 v[10:11], 0
	v_mov_b64_e32 v[12:13], 0
	v_mov_b64_e32 v[14:15], 0
	v_mov_b64_e32 v[16:17], 0
	v_mov_b64_e32 v[18:19], 0
	v_mov_b64_e32 v[20:21], 0
	v_mov_b64_e32 v[22:23], 0
	v_mov_b64_e32 v[24:25], 0
	v_mov_b64_e32 v[26:27], 0
	v_mov_b64_e32 v[28:29], 0
	v_mov_b64_e32 v[30:31], 0
	v_mov_b64_e32 v[32:33], 0
	v_mov_b64_e32 v[34:35], 0
	v_mov_b64_e32 v[36:37], 0
	v_mov_b64_e32 v[38:39], 0
	v_mov_b64_e32 v[40:41], 0
	v_mov_b64_e32 v[42:43], 0
	v_mov_b64_e32 v[44:45], 0
	v_mov_b64_e32 v[46:47], 0
	v_mov_b64_e32 v[48:49], 0
	v_mov_b64_e32 v[50:51], 0
	v_mov_b64_e32 v[52:53], 0
	v_mov_b64_e32 v[54:55], 0
	v_mov_b64_e32 v[56:57], 0
	v_mov_b64_e32 v[58:59], 0
	v_mov_b64_e32 v[60:61], 0
	v_mov_b64_e32 v[62:63], 0
	v_mov_b64_e32 v[64:65], 0
	v_mov_b64_e32 v[66:67], 0
	v_mov_b64_e32 v[68:69], 0
	v_mov_b64_e32 v[70:71], 0
	v_mov_b64_e32 v[72:73], 0
	v_mov_b64_e32 v[74:75], 0
	v_mov_b64_e32 v[76:77], 0
	v_mov_b64_e32 v[78:79], 0
	v_mov_b64_e32 v[80:81], 0
	v_mov_b64_e32 v[82:83], 0
	v_mov_b64_e32 v[84:85], 0
	v_mov_b64_e32 v[86:87], 0
	v_mov_b64_e32 v[88:89], 0
	v_mov_b64_e32 v[90:91], 0
	v_mov_b64_e32 v[92:93], 0
	v_mov_b64_e32 v[94:95], 0
	v_mov_b64_e32 v[96:97], 0
	v_mov_b64_e32 v[98:99], 0
	v_mov_b64_e32 v[100:101], 0
	v_mov_b64_e32 v[102:103], 0
	v_mov_b64_e32 v[104:105], 0
	v_mov_b64_e32 v[106:107], 0
	v_mov_b64_e32 v[108:109], 0
	v_mov_b64_e32 v[110:111], 0
	v_mov_b64_e32 v[112:113], 0
	v_mov_b64_e32 v[114:115], 0
	v_mov_b64_e32 v[116:117], 0
	v_mov_b64_e32 v[118:119], 0
	v_mov_b64_e32 v[120:121], 0
	v_mov_b64_e32 v[122:123], 0
	v_mov_b64_e32 v[124:125], 0
	v_mov_b64_e32 v[126:127], 0
	v_mov_b64_e32 v[128:129], 0
	v_mov_b64_e32 v[130:131], 0
	v_mov_b64_e32 v[132:133], 0
	v_mov_b64_e32 v[134:135], 0
	v_mov_b64_e32 v[136:137], 0

; template <class Epi, class Sched, bool ALIGN_EPI = false, bool SP2 = false>
; __device__ __forceinline__ void gemm_phase(PG8_LAS unsigned char* lds, const Gemm g, const Sched& S, const Epi& E) {
;     ...
;         const char* nA = has_next ? (const char*)g.A + (size_t)nxt.pm * tstep : cA; const char* nB = has_next ? (const char*)g.Bt + (size_t)nxt.pn * tstep : cB;
;         for (int t = 0; t < nt; t += 2) {
;             const bool last = (t == nt - 2);
;             const char* a1 = cA + (size_t)(t + 1) * kstep;
;             const char* a2 = last ? nA : cA + (size_t)(t + 2) * kstep; const char* b2 = last ? nB : cB + (size_t)(t + 2) * kstep;
;     ...
;         for (int a = 0; a < 2; ++a)
; #pragma unroll
;             for (int b = 0; b < 2; ++b)
; #pragma unroll
;                 for (int m = 0; m < 4; ++m)
; #pragma unroll
;                     for (int n = 0; n < 2; ++n) acc[a][b][m][n] = (f32x4){0.f, 0.f, 0.f, 0.f};
.LBB0_1061:
	s_ashr_i32 s63, s62, 31
	s_lshl_b64 s[34:35], s[62:63], 20
	s_add_u32 s64, s14, s34
	s_addc_u32 s65, s15, s35
	s_and_b64 s[34:35], s[4:5], exec
	s_cselect_b32 s34, s65, s71
	s_cselect_b32 s35, s64, s70
	s_ashr_i32 s61, s60, 31
	s_lshl_b64 s[66:67], s[60:61], 20
	s_add_u32 s66, s46, s66
	s_addc_u32 s67, s47, s67
	s_and_b64 s[74:75], s[4:5], exec
	s_cselect_b32 s61, s67, s73
	s_cselect_b32 s63, s66, s72
	s_add_u32 s70, s70, 0x80080
	s_addc_u32 s71, s71, 0
	s_add_u32 s69, s72, 0x100
	v_mov_b32_e32 v2, 0
	s_addc_u32 s76, s73, 0
	s_mov_b32 s77, -2
	v_mov_b64_e32 v[2:3], 0
	v_mov_b64_e32 v[4:5], 0
	v_mov_b64_e32 v[6:7], 0
	v_mov_b64_e32 v[8:9], 0
	v_mov_b64_e32 v[10:11], 0
	v_mov_b64_e32 v[12:13], 0
	v_mov_b64_e32 v[14:15], 0
	v_mov_b64_e32 v[16:17], 0
	v_mov_b64_e32 v[18:19], 0
	v_mov_b64_e32 v[20:21], 0
	v_mov_b64_e32 v[22:23], 0
	v_mov_b64_e32 v[24:25], 0
	v_mov_b64_e32 v[26:27], 0
	v_mov_b64_e32 v[28:29], 0
	v_mov_b64_e32 v[30:31], 0
	v_mov_b64_e32 v[32:33], 0
	v_mov_b64_e32 v[34:35], 0
	v_mov_b64_e32 v[36:37], 0
	v_mov_b64_e32 v[38:39], 0
	v_mov_b64_e32 v[40:41], 0
	v_mov_b64_e32 v[42:43], 0
	v_mov_b64_e32 v[44:45], 0
	v_mov_b64_e32 v[46:47], 0
	v_mov_b64_e32 v[48:49], 0
	v_mov_b64_e32 v[50:51], 0
	v_mov_b64_e32 v[52:53], 0
	v_mov_b64_e32 v[54:55], 0
	v_mov_b64_e32 v[56:57], 0
	v_mov_b64_e32 v[58:59], 0
	v_mov_b64_e32 v[60:61], 0
	v_mov_b64_e32 v[62:63], 0
	v_mov_b64_e32 v[64:65], 0
	v_mov_b64_e32 v[66:67], 0
	v_mov_b64_e32 v[68:69], 0
	v_mov_b64_e32 v[70:71], 0
	v_mov_b64_e32 v[72:73], 0
	v_mov_b64_e32 v[74:75], 0
	v_mov_b64_e32 v[76:77], 0
	v_mov_b64_e32 v[78:79], 0
	v_mov_b64_e32 v[80:81], 0
	v_mov_b64_e32 v[82:83], 0
	v_mov_b64_e32 v[84:85], 0
	v_mov_b64_e32 v[86:87], 0
	v_mov_b64_e32 v[88:89], 0
	v_mov_b64_e32 v[90:91], 0
	v_mov_b64_e32 v[92:93], 0
	v_mov_b64_e32 v[94:95], 0
	v_mov_b64_e32 v[96:97], 0
	v_mov_b64_e32 v[98:99], 0
	v_mov_b64_e32 v[100:101], 0
	v_mov_b64_e32 v[102:103], 0
	v_mov_b64_e32 v[104:105], 0
	v_mov_b64_e32 v[106:107], 0
	v_mov_b64_e32 v[108:109], 0
	v_mov_b64_e32 v[110:111], 0
	v_mov_b64_e32 v[112:113], 0
	v_mov_b64_e32 v[114:115], 0
	v_mov_b64_e32 v[116:117], 0
	v_mov_b64_e32 v[118:119], 0
	v_mov_b64_e32 v[120:121], 0
	v_mov_b64_e32 v[122:123], 0
	v_mov_b64_e32 v[124:125], 0
	v_mov_b64_e32 v[126:127], 0
	v_mov_b64_e32 v[128:129], 0

; template <class Epi, class Sched, bool ALIGN_EPI = false, bool SP2 = false>
; __device__ __forceinline__ void gemm_phase(PG8_LAS unsigned char* lds, const Gemm g, const Sched& S, const Epi& E) {
;     ...
;         const char* nA = has_next ? (const char*)g.A + (size_t)nxt.pm * tstep : cA; const char* nB = has_next ? (const char*)g.Bt + (size_t)nxt.pn * tstep : cB;
;         for (int t = 0; t < nt; t += 2) {
;             const bool last = (t == nt - 2);
;             const char* a1 = cA + (size_t)(t + 1) * kstep;
;             const char* a2 = last ? nA : cA + (size_t)(t + 2) * kstep; const char* b2 = last ? nB : cB + (size_t)(t + 2) * kstep;
;     ...
;         for (int a = 0; a < 2; ++a)
; #pragma unroll
;             for (int b = 0; b < 2; ++b)
; #pragma unroll
;                 for (int m = 0; m < 4; ++m)
; #pragma unroll
;                     for (int n = 0; n < 2; ++n) acc[a][b][m][n] = (f32x4){0.f, 0.f, 0.f, 0.f};
.LBB0_1077:
	s_ashr_i32 s59, s58, 31
	s_lshl_b64 s[34:35], s[58:59], 20
	s_add_u32 s60, s42, s34
	s_addc_u32 s61, s43, s35
	s_and_b64 s[34:35], s[4:5], exec
	s_cselect_b32 s34, s61, s67
	s_cselect_b32 s35, s60, s66
	s_ashr_i32 s57, s56, 31
	s_lshl_b64 s[62:63], s[56:57], 20
	s_add_u32 s62, s44, s62
	s_addc_u32 s63, s45, s63
	s_and_b64 s[70:71], s[4:5], exec
	s_cselect_b32 s57, s63, s69
	s_cselect_b32 s59, s62, s68
	s_add_u32 s66, s66, 0x80080
	s_addc_u32 s67, s67, 0
	s_add_u32 s65, s68, 0x100
	v_mov_b32_e32 v2, 0
	s_addc_u32 s72, s69, 0
	s_mov_b32 s73, -2
	v_mov_b64_e32 v[2:3], 0
	v_mov_b64_e32 v[4:5], 0
	v_mov_b64_e32 v[6:7], 0
	v_mov_b64_e32 v[8:9], 0
	v_mov_b64_e32 v[10:11], 0
	v_mov_b64_e32 v[12:13], 0
	v_mov_b64_e32 v[14:15], 0
	v_mov_b64_e32 v[16:17], 0
	v_mov_b64_e32 v[18:19], 0
	v_mov_b64_e32 v[20:21], 0
	v_mov_b64_e32 v[22:23], 0
	v_mov_b64_e32 v[24:25], 0
	v_mov_b64_e32 v[26:27], 0
	v_mov_b64_e32 v[28:29], 0
	v_mov_b64_e32 v[30:31], 0
	v_mov_b64_e32 v[32:33], 0
	v_mov_b64_e32 v[34:35], 0
	v_mov_b64_e32 v[36:37], 0
	v_mov_b64_e32 v[38:39], 0
	v_mov_b64_e32 v[40:41], 0
	v_mov_b64_e32 v[42:43], 0
	v_mov_b64_e32 v[44:45], 0
	v_mov_b64_e32 v[46:47], 0
	v_mov_b64_e32 v[48:49], 0
	v_mov_b64_e32 v[50:51], 0
	v_mov_b64_e32 v[52:53], 0
	v_mov_b64_e32 v[54:55], 0
	v_mov_b64_e32 v[56:57], 0
	v_mov_b64_e32 v[58:59], 0
	v_mov_b64_e32 v[60:61], 0
	v_mov_b64_e32 v[62:63], 0
	v_mov_b64_e32 v[64:65], 0
	v_mov_b64_e32 v[66:67], 0
	v_mov_b64_e32 v[68:69], 0
	v_mov_b64_e32 v[70:71], 0
	v_mov_b64_e32 v[72:73], 0
	v_mov_b64_e32 v[74:75], 0
	v_mov_b64_e32 v[76:77], 0
	v_mov_b64_e32 v[78:79], 0
	v_mov_b64_e32 v[80:81], 0
	v_mov_b64_e32 v[82:83], 0
	v_mov_b64_e32 v[84:85], 0
	v_mov_b64_e32 v[86:87], 0
	v_mov_b64_e32 v[88:89], 0
	v_mov_b64_e32 v[90:91], 0
	v_mov_b64_e32 v[92:93], 0
	v_mov_b64_e32 v[94:95], 0
	v_mov_b64_e32 v[96:97], 0
	v_mov_b64_e32 v[98:99], 0
	v_mov_b64_e32 v[100:101], 0
	v_mov_b64_e32 v[102:103], 0
	v_mov_b64_e32 v[104:105], 0
	v_mov_b64_e32 v[106:107], 0
	v_mov_b64_e32 v[108:109], 0
	v_mov_b64_e32 v[110:111], 0
	v_mov_b64_e32 v[112:113], 0
	v_mov_b64_e32 v[114:115], 0
	v_mov_b64_e32 v[116:117], 0
	v_mov_b64_e32 v[118:119], 0
	v_mov_b64_e32 v[120:121], 0
	v_mov_b64_e32 v[122:123], 0
	v_mov_b64_e32 v[124:125], 0
	v_mov_b64_e32 v[126:127], 0
	v_mov_b64_e32 v[128:129], 0

; template <class Epi, class Sched, bool ALIGN_EPI = false, bool SP2 = false>
; __device__ __forceinline__ void gemm_phase(PG8_LAS unsigned char* lds, const Gemm g, const Sched& S, const Epi& E) {
;     ...
;         const char* nA = has_next ? (const char*)g.A + (size_t)nxt.pm * tstep : cA; const char* nB = has_next ? (const char*)g.Bt + (size_t)nxt.pn * tstep : cB;
;         for (int t = 0; t < nt; t += 2) {
;             const bool last = (t == nt - 2);
;             const char* a1 = cA + (size_t)(t + 1) * kstep;
;             const char* a2 = last ? nA : cA + (size_t)(t + 2) * kstep; const char* b2 = last ? nB : cB + (size_t)(t + 2) * kstep;
;     ...
;         for (int a = 0; a < 2; ++a)
; #pragma unroll
;             for (int b = 0; b < 2; ++b)
; #pragma unroll
;                 for (int m = 0; m < 4; ++m)
; #pragma unroll
;                     for (int n = 0; n < 2; ++n) acc[a][b][m][n] = (f32x4){0.f, 0.f, 0.f, 0.f};
.LBB0_1202:
	s_ashr_i32 s55, s54, 31
	s_lshl_b64 s[34:35], s[54:55], 21
	s_add_u32 s56, s36, s34
	s_addc_u32 s57, s37, s35
	s_and_b64 s[34:35], s[8:9], exec
	s_cselect_b32 s34, s57, s65
	s_cselect_b32 s35, s56, s64
	s_ashr_i32 s53, s52, 31
	s_lshl_b64 s[40:41], s[52:53], 21
	s_add_u32 s58, s12, s40
	s_addc_u32 s59, s13, s41
	s_and_b64 s[40:41], s[8:9], exec
	s_cselect_b32 s40, s59, s67
	s_cselect_b32 s41, s58, s66
	s_add_u32 s64, s64, 0x100080
	s_addc_u32 s65, s65, 0
	s_add_u32 s53, s66, 0x100
	v_mov_b32_e32 v2, 0
	s_addc_u32 s55, s67, 0
	s_mov_b32 s61, -2
	s_waitcnt lgkmcnt(0)
	v_mov_b64_e32 v[2:3], 0
	v_mov_b64_e32 v[4:5], 0
	v_mov_b64_e32 v[6:7], 0
	v_mov_b64_e32 v[8:9], 0
	v_mov_b64_e32 v[10:11], 0
	v_mov_b64_e32 v[12:13], 0
	v_mov_b64_e32 v[14:15], 0
	v_mov_b64_e32 v[16:17], 0
	v_mov_b64_e32 v[18:19], 0
	v_mov_b64_e32 v[20:21], 0
	v_mov_b64_e32 v[22:23], 0
	v_mov_b64_e32 v[24:25], 0
	v_mov_b64_e32 v[26:27], 0
	v_mov_b64_e32 v[28:29], 0
	v_mov_b64_e32 v[30:31], 0
	v_mov_b64_e32 v[32:33], 0
	v_mov_b64_e32 v[34:35], 0
	v_mov_b64_e32 v[36:37], 0
	v_mov_b64_e32 v[38:39], 0
	v_mov_b64_e32 v[40:41], 0
	v_mov_b64_e32 v[42:43], 0
	v_mov_b64_e32 v[44:45], 0
	v_mov_b64_e32 v[46:47], 0
	v_mov_b64_e32 v[48:49], 0
	v_mov_b64_e32 v[50:51], 0
	v_mov_b64_e32 v[52:53], 0
	v_mov_b64_e32 v[54:55], 0
	v_mov_b64_e32 v[56:57], 0
	v_mov_b64_e32 v[58:59], 0
	v_mov_b64_e32 v[60:61], 0
	v_mov_b64_e32 v[62:63], 0
	v_mov_b64_e32 v[64:65], 0
	v_mov_b64_e32 v[66:67], 0
	v_mov_b64_e32 v[68:69], 0
	v_mov_b64_e32 v[70:71], 0
	v_mov_b64_e32 v[72:73], 0
	v_mov_b64_e32 v[74:75], 0
	v_mov_b64_e32 v[76:77], 0
	v_mov_b64_e32 v[78:79], 0
	v_mov_b64_e32 v[80:81], 0
	v_mov_b64_e32 v[82:83], 0
	v_mov_b64_e32 v[84:85], 0
	v_mov_b64_e32 v[86:87], 0
	v_mov_b64_e32 v[88:89], 0
	v_mov_b64_e32 v[90:91], 0
	v_mov_b64_e32 v[92:93], 0
	v_mov_b64_e32 v[94:95], 0
	v_mov_b64_e32 v[96:97], 0
	v_mov_b64_e32 v[98:99], 0
	v_mov_b64_e32 v[100:101], 0
	v_mov_b64_e32 v[102:103], 0
	v_mov_b64_e32 v[104:105], 0
	v_mov_b64_e32 v[106:107], 0
	v_mov_b64_e32 v[108:109], 0
	v_mov_b64_e32 v[110:111], 0
	v_mov_b64_e32 v[112:113], 0
	v_mov_b64_e32 v[114:115], 0
	v_mov_b64_e32 v[116:117], 0
	v_mov_b64_e32 v[118:119], 0
	v_mov_b64_e32 v[120:121], 0
	v_mov_b64_e32 v[122:123], 0
	v_mov_b64_e32 v[124:125], 0
	v_mov_b64_e32 v[126:127], 0
	v_mov_b64_e32 v[128:129], 0

; #define PG8_STAGE(bufoff, gbase, voff) do { _Pragma("unroll") for (int _i = 0; _i < 2; ++_i) \
;         __builtin_amdgcn_global_load_lds((const unsigned*)((const char*)(gbase) + (voff)[_i]), (PG8_LAS unsigned*)(lds + (bufoff) + ldsw + _i * 8192), 16, 0, 0); } while (0)
; #define PG8_WAIT_V(n) asm volatile("s_waitcnt vmcnt(" #n ")" ::: "memory")
; #define PG8_BAR __builtin_amdgcn_s_barrier()
;     __device__ __forceinline__ bool next(int i, Unit& u) const { if (!pg8::StaticOrder::next(i, u)) return false; if (u.pn >= 32) u.pn += 1; return true; }
;     __device__ __forceinline__ bool next(int i, Unit& u) const { if (i > 0 || c >= 204) return false; u.pm = c % 68; u.pn = 32; return true; }
;     __device__ __forceinline__ bool next(int i, Unit& u) const { if (i > 0) return false; u.pm = 64 + ((c & 63) >> 4); u.pn = c & 15; return true; }
; template <class Epi, class Sched, bool ALIGN_EPI = false, bool SP2 = false>
; __device__ __forceinline__ void gemm_phase(PG8_LAS unsigned char* lds, const Gemm g, const Sched& S, const Epi& E) {
;     ...
;     const int aoff = lds_byte(wr * 64 + fr, fq * 8), boff = lds_byte(wc * 32 + fr, fq * 8);
;     ...
;     Unit cur, nxt; int ui = 0;
;     if (!S.next(0, cur)) return;
;     f32x4 acc[2][2][4][2];
; #pragma unroll
;     for (int a = 0; a < 2; ++a)
; #pragma unroll
;         for (int b = 0; b < 2; ++b)
; #pragma unroll
;             for (int m = 0; m < 4; ++m)
; #pragma unroll
;                 for (int n = 0; n < 2; ++n) acc[a][b][m][n] = (f32x4){0.f, 0.f, 0.f, 0.f};
;     bf16x8 At[4][2], B0[2][2], B1[2][2];
;     const char* cA = (const char*)g.A + (size_t)cur.pm * tstep; const char* cB = (const char*)g.Bt + (size_t)cur.pn * tstep;
;     S.a_ready(cur);
;     if constexpr (SP2) {
;         PG8_STAGE(PG8_SB(0, 0), cB, voffB); PG8_STAGE(PG8_SB(0, 1), cB + hstep, voffB); PG8_STAGE(PG8_SA(0, 0), cA, voffA); PG8_STAGE(PG8_SA(0, 1), cA + hstep, voffA);
;         if (wr == 1) PG8_BAR;
;         PG8_WAIT_V(2); PG8_BAR;
;         PG8_STAGE(PG8_SB(1, 0), cB + kstep, voffB); PG8_STAGE(PG8_SA(1, 0), cA + kstep, voffA); PG8_STAGE(PG8_SB(1, 1), cB + hstep + kstep, voffB);
;         PG8_WAIT_V(6); PG8_BAR;
.LBB0_1229:
	v_bfe_u32 v138, v18, 4, 2
	s_lshl_b32 s13, s13, 5
	v_and_b32_e32 v139, 15, v18
	v_lshlrev_b32_e32 v19, 4, v138
	s_and_b32 s27, s13, 0x60
	v_lshlrev_b32_e32 v18, 2, v18
	s_lshl_b32 s25, s12, 6
	v_lshl_or_b32 v19, v139, 6, v19
	s_lshl_b32 s13, s27, 7
	v_and_b32_e32 v18, 32, v18
	s_lshl_b32 s12, s12, 13
	v_bitop3_b32 v20, v19, s13, v18 bitop3:0xde
	v_bitop3_b32 v18, v19, s12, v18 bitop3:0xde
	s_mov_b64 s[12:13], 0x80
	s_add_i32 m0, s7, 0x18000
	v_lshl_add_u64 v[8:9], v[8:9], 0, s[12:13]
	s_waitcnt vmcnt(2)
	s_barrier
	global_load_lds_dwordx4 v[8:9], off
	v_lshl_add_u64 v[6:7], v[6:7], 0, s[12:13]
	s_add_i32 m0, s7, 0x1a000
	s_add_i32 s28, s7, 0x8000
	s_add_i32 s29, s7, 0xa000
	global_load_lds_dwordx4 v[6:7], off
	v_lshl_add_u64 v[4:5], v[4:5], 0, s[12:13]
	s_mov_b32 m0, s28
	s_add_u32 s34, s8, 0x100080
	global_load_lds_dwordx4 v[4:5], off
	v_lshl_add_u64 v[2:3], v[2:3], 0, s[12:13]
	s_mov_b32 m0, s29
	s_addc_u32 s35, s9, 0
	global_load_lds_dwordx4 v[2:3], off
	s_add_i32 m0, s7, 0x1c000
	v_lshl_add_u64 v[2:3], s[34:35], 0, v[130:131]
	global_load_lds_dwordx4 v[2:3], off
	v_lshl_add_u64 v[2:3], s[34:35], 0, v[132:133]
	s_add_i32 m0, s7, 0x1e000
	s_lshl_b32 s30, s96, 17
	global_load_lds_dwordx4 v[2:3], off
	s_and_b32 s30, s30, 0x600000
	v_lshlrev_b32_e32 v2, 15, v10
	s_add_u32 s30, s30, s46
	v_and_b32_e32 v2, 0x7fff0000, v2
	s_addc_u32 s33, 0, s47
	v_lshl_add_u32 v2, v11, 12, v2
	v_or_b32_e32 v2, v2, v12
	s_add_u32 s34, s22, s30
	v_add_lshl_u32 v2, v2, v14, 1
	v_mov_b32_e32 v3, v131
	s_addc_u32 s35, s23, s33
	v_lshl_add_u64 v[2:3], s[34:35], 0, v[2:3]
	s_mov_b64 s[40:41], 0x24d00080
	v_lshl_add_u64 v[134:135], v[2:3], 0, s[40:41]
	v_lshlrev_b32_e32 v2, 15, v13
	v_and_b32_e32 v2, 0x7fff0000, v2
	v_lshl_add_u32 v2, v15, 12, v2
	v_or_b32_e32 v2, v2, v16
	v_add_lshl_u32 v2, v2, v17, 1
	v_mov_b32_e32 v3, v131
	v_lshl_add_u64 v[2:3], s[34:35], 0, v[2:3]
	s_waitcnt vmcnt(6)
	v_lshl_add_u64 v[136:137], v[2:3], 0, s[40:41]
	s_add_i32 s40, 0, 0x14000
	s_add_i32 s44, 0, 0x18000
	s_add_i32 s56, 0, 0x1c000
	s_waitcnt vmcnt(0)
	v_add_u32_e32 v141, s40, v20
	s_add_i32 s35, s31, s50
	s_add_i32 s40, s40, s50
	v_add_u32_e32 v143, s44, v20
	v_add_u32_e32 v144, s56, v20
	s_add_i32 s44, s44, s50
	s_add_i32 s56, s56, s50
	s_mov_b32 s30, -2
	s_mov_b64 s[46:47], 0
	v_add_u32_e32 v140, s31, v20
	v_add_u32_e32 v142, 0, v18
	s_add_i32 s33, s7, 0xc000
	s_add_i32 s34, s7, 0xe000
	s_add_i32 s39, s35, 0x2000
	s_add_i32 s41, s40, 0x2000
	s_add_i32 s45, s44, 0x2000
	s_add_i32 s57, s56, 0x2000
	v_mov_b64_e32 v[2:3], 0
	v_mov_b64_e32 v[4:5], 0
	v_mov_b64_e32 v[6:7], 0
	v_mov_b64_e32 v[8:9], 0
	v_mov_b64_e32 v[10:11], 0
	v_mov_b64_e32 v[12:13], 0
	v_mov_b64_e32 v[14:15], 0
	v_mov_b64_e32 v[16:17], 0
	v_mov_b64_e32 v[18:19], 0
	v_mov_b64_e32 v[20:21], 0
	v_mov_b64_e32 v[22:23], 0
	v_mov_b64_e32 v[24:25], 0
	v_mov_b64_e32 v[26:27], 0
	v_mov_b64_e32 v[28:29], 0
	v_mov_b64_e32 v[30:31], 0
	v_mov_b64_e32 v[32:33], 0
	v_mov_b64_e32 v[34:35], 0
	v_mov_b64_e32 v[36:37], 0
	v_mov_b64_e32 v[38:39], 0
	v_mov_b64_e32 v[40:41], 0
	v_mov_b64_e32 v[42:43], 0
	v_mov_b64_e32 v[44:45], 0
	v_mov_b64_e32 v[46:47], 0
	v_mov_b64_e32 v[48:49], 0
	v_mov_b64_e32 v[50:51], 0
	v_mov_b64_e32 v[52:53], 0
	v_mov_b64_e32 v[54:55], 0
	v_mov_b64_e32 v[56:57], 0
	v_mov_b64_e32 v[58:59], 0
	v_mov_b64_e32 v[60:61], 0
	v_mov_b64_e32 v[62:63], 0
	v_mov_b64_e32 v[64:65], 0
	v_mov_b64_e32 v[66:67], 0
	v_mov_b64_e32 v[68:69], 0
	v_mov_b64_e32 v[70:71], 0
	v_mov_b64_e32 v[72:73], 0
	v_mov_b64_e32 v[74:75], 0
	v_mov_b64_e32 v[76:77], 0
	v_mov_b64_e32 v[78:79], 0
	v_mov_b64_e32 v[80:81], 0
	v_mov_b64_e32 v[82:83], 0
	v_mov_b64_e32 v[84:85], 0
	v_mov_b64_e32 v[86:87], 0
	v_mov_b64_e32 v[88:89], 0
	v_mov_b64_e32 v[90:91], 0
	v_mov_b64_e32 v[92:93], 0
	v_mov_b64_e32 v[94:95], 0
	v_mov_b64_e32 v[96:97], 0
	v_mov_b64_e32 v[98:99], 0
	v_mov_b64_e32 v[100:101], 0
	v_mov_b64_e32 v[102:103], 0
	v_mov_b64_e32 v[104:105], 0
	v_mov_b64_e32 v[106:107], 0
	v_mov_b64_e32 v[108:109], 0
	v_mov_b64_e32 v[110:111], 0
	v_mov_b64_e32 v[112:113], 0
	v_mov_b64_e32 v[114:115], 0
	v_mov_b64_e32 v[116:117], 0
	v_mov_b64_e32 v[118:119], 0
	v_mov_b64_e32 v[120:121], 0
	v_mov_b64_e32 v[122:123], 0
	v_mov_b64_e32 v[124:125], 0
	v_mov_b64_e32 v[126:127], 0
	v_mov_b64_e32 v[128:129], 0
	v_mov_b32_e32 v131, 0
	s_barrier

; template <class Epi, class Sched, bool ALIGN_EPI = false, bool SP2 = false>
; __device__ __forceinline__ void gemm_phase(PG8_LAS unsigned char* lds, const Gemm g, const Sched& S, const Epi& E) {
;     ...
;         const char* nA = has_next ? (const char*)g.A + (size_t)nxt.pm * tstep : cA; const char* nB = has_next ? (const char*)g.Bt + (size_t)nxt.pn * tstep : cB;
;         for (int t = 0; t < nt; t += 2) {
;             const bool last = (t == nt - 2);
;             const char* a1 = cA + (size_t)(t + 1) * kstep;
;             const char* a2 = last ? nA : cA + (size_t)(t + 2) * kstep; const char* b2 = last ? nB : cB + (size_t)(t + 2) * kstep;
;             const char* a3 = a2 + kstep; const char* b3 = b2 + kstep;
;             if (last && has_next) S.a_ready(nxt);
;     ...
;         for (int a = 0; a < 2; ++a)
; #pragma unroll
;             for (int b = 0; b < 2; ++b)
; #pragma unroll
;                 for (int m = 0; m < 4; ++m)
; #pragma unroll
;                     for (int n = 0; n < 2; ++n) acc[a][b][m][n] = (f32x4){0.f, 0.f, 0.f, 0.f};
.LBB0_1476:
	s_mov_b32 s68, s35
	s_ashr_i32 s69, s35, 31
	s_mov_b32 s66, s34
	s_lshl_b64 s[34:35], s[68:69], 21
	s_add_u32 s72, s14, s34
	s_addc_u32 s73, s15, s35
	s_and_b64 s[34:35], s[70:71], exec
	s_mov_b32 s5, s65
	s_cselect_b32 s65, s73, s83
	s_cselect_b32 s69, s72, s82
	s_ashr_i32 s67, s66, 31
	s_lshl_b64 s[34:35], s[66:67], 21
	v_readlane_b32 s48, v255, 10
	v_readlane_b32 s49, v255, 11
	s_add_u32 s74, s48, s34
	s_addc_u32 s75, s49, s35
	s_and_b64 s[34:35], s[70:71], exec
	s_cselect_b32 s67, s75, s85
	s_cselect_b32 s77, s74, s84
	s_lshl_b32 s34, s68, 8
	s_lshl_b32 s80, s66, 7
	s_ashr_i32 s35, s34, 31
	s_ashr_i32 s81, s80, 31
	s_add_u32 s82, s82, 0x100080
	s_addc_u32 s83, s83, 0
	s_add_u32 s79, s84, 0x100
	v_mov_b32_e32 v18, 0
	v_lshl_add_u64 v[130:131], s[34:35], 2, v[218:219]
	s_addc_u32 s88, s85, 0
	s_mov_b32 s89, -2
	v_mov_b64_e32 v[2:3], 0
	v_mov_b64_e32 v[4:5], 0
	v_mov_b64_e32 v[6:7], 0
	v_mov_b64_e32 v[8:9], 0
	v_mov_b64_e32 v[10:11], 0
	v_mov_b64_e32 v[12:13], 0
	v_mov_b64_e32 v[14:15], 0
	v_mov_b64_e32 v[16:17], 0
	v_mov_b64_e32 v[18:19], 0
	v_mov_b64_e32 v[20:21], 0
	v_mov_b64_e32 v[22:23], 0
	v_mov_b64_e32 v[24:25], 0
	v_mov_b64_e32 v[26:27], 0
	v_mov_b64_e32 v[28:29], 0
	v_mov_b64_e32 v[30:31], 0
	v_mov_b64_e32 v[32:33], 0
	v_mov_b64_e32 v[34:35], 0
	v_mov_b64_e32 v[36:37], 0
	v_mov_b64_e32 v[38:39], 0
	v_mov_b64_e32 v[40:41], 0
	v_mov_b64_e32 v[42:43], 0
	v_mov_b64_e32 v[44:45], 0
	v_mov_b64_e32 v[46:47], 0
	v_mov_b64_e32 v[48:49], 0
	v_mov_b64_e32 v[50:51], 0
	v_mov_b64_e32 v[52:53], 0
	v_mov_b64_e32 v[54:55], 0
	v_mov_b64_e32 v[56:57], 0
	v_mov_b64_e32 v[58:59], 0
	v_mov_b64_e32 v[60:61], 0
	v_mov_b64_e32 v[62:63], 0
	v_mov_b64_e32 v[64:65], 0
	v_mov_b64_e32 v[66:67], 0
	v_mov_b64_e32 v[68:69], 0
	v_mov_b64_e32 v[70:71], 0
	v_mov_b64_e32 v[72:73], 0
	v_mov_b64_e32 v[74:75], 0
	v_mov_b64_e32 v[76:77], 0
	v_mov_b64_e32 v[78:79], 0
	v_mov_b64_e32 v[80:81], 0
	v_mov_b64_e32 v[82:83], 0
	v_mov_b64_e32 v[84:85], 0
	v_mov_b64_e32 v[86:87], 0
	v_mov_b64_e32 v[88:89], 0
	v_mov_b64_e32 v[90:91], 0
	v_mov_b64_e32 v[92:93], 0
	v_mov_b64_e32 v[94:95], 0
	v_mov_b64_e32 v[96:97], 0
	v_mov_b64_e32 v[98:99], 0
	v_mov_b64_e32 v[100:101], 0
	v_mov_b64_e32 v[102:103], 0
	v_mov_b64_e32 v[104:105], 0
	v_mov_b64_e32 v[106:107], 0
	v_mov_b64_e32 v[108:109], 0
	v_mov_b64_e32 v[110:111], 0
	v_mov_b64_e32 v[112:113], 0
	v_mov_b64_e32 v[114:115], 0
	v_mov_b64_e32 v[116:117], 0
	v_mov_b64_e32 v[118:119], 0
	v_mov_b64_e32 v[120:121], 0
	v_mov_b64_e32 v[122:123], 0
	v_mov_b64_e32 v[124:125], 0
	v_mov_b64_e32 v[126:127], 0
	v_mov_b64_e32 v[128:129], 0
	s_branch .LBB0_1479

; #define PG8_STAGE(bufoff, gbase, voff) do { _Pragma("unroll") for (int _i = 0; _i < 2; ++_i) \
;         __builtin_amdgcn_global_load_lds((const unsigned*)((const char*)(gbase) + (voff)[_i]), (PG8_LAS unsigned*)(lds + (bufoff) + ldsw + _i * 8192), 16, 0, 0); } while (0)
; #define PG8_LDA(dst, b, h) do { _Pragma("unroll") for (int m = 0; m < 4; ++m) _Pragma("unroll") for (int k = 0; k < 2; ++k) dst[m][k] = *(const PG8_LAS bf16x8*)(lds + PG8_SA(b, h) + aoff + m * 2048 + k * 1024); } while (0)
; #define PG8_LDB(dst, b, h) do { _Pragma("unroll") for (int n = 0; n < 2; ++n) _Pragma("unroll") for (int k = 0; k < 2; ++k) dst[n][k] = *(const PG8_LAS bf16x8*)(lds + PG8_SB(b, h) + boff + n * 2048 + k * 1024); } while (0)
; #define PG8_MMA(ai, bj, At, Bt) do { __builtin_amdgcn_s_setprio(1); _Pragma("unroll") for (int m = 0; m < 4; ++m) _Pragma("unroll") for (int n = 0; n < 2; ++n) _Pragma("unroll") for (int k = 0; k < 2; ++k) \
;         acc[ai][bj][m][n] = __builtin_amdgcn_mfma_f32_16x16x32_bf16(Bt[n][k], At[m][k], acc[ai][bj][m][n], 0, 0, 0); __builtin_amdgcn_s_setprio(0); } while (0)
; #define PG8_WAIT_V(n) asm volatile("s_waitcnt vmcnt(" #n ")" ::: "memory")
; #define PG8_WAIT_L(n) asm volatile("s_waitcnt lgkmcnt(" #n ")" ::: "memory")
; #define PG8_BAR __builtin_amdgcn_s_barrier()
; #define PG8_SCHED __builtin_amdgcn_sched_barrier(0)
; template <class Epi, class Sched, bool ALIGN_EPI = false, bool SP2 = false>
; __device__ __forceinline__ void gemm_phase(PG8_LAS unsigned char* lds, const Gemm g, const Sched& S, const Epi& E) {
;     ...
;             PG8_LDB(B0, 0, 0); PG8_LDB(B1, 0, 1); PG8_SCHED; PG8_LDA(At, 0, 0); PG8_STAGE(PG8_SA(1, 1), a1 + hstep, voffA);
;             PG8_WAIT_V(8); PG8_WAIT_L(0); PG8_BAR; PG8_MMA(0, 0, At, B0); PG8_MMA(0, 1, At, B1); PG8_BAR; PG8_SCHED;
;             PG8_LDA(At, 0, 1); PG8_STAGE(PG8_SB(0, 0), b2, voffB); PG8_STAGE(PG8_SB(0, 1), b2 + hstep, voffB); PG8_STAGE(PG8_SA(0, 0), a2, voffA);
;             PG8_WAIT_V(8); PG8_WAIT_L(0); PG8_BAR; PG8_MMA(1, 0, At, B0); PG8_MMA(1, 1, At, B1); PG8_BAR; PG8_SCHED;
.LBB0_1478:
	v_add_u32_e32 v144, s31, v201
	v_add_u32_e32 v160, s52, v201
	ds_read_b128 v[132:135], v144
	ds_read_b128 v[136:139], v144 offset:1024
	ds_read_b128 v[140:143], v144 offset:2048
	ds_read_b128 v[144:147], v144 offset:3072
	ds_read_b128 v[148:151], v160
	ds_read_b128 v[152:155], v160 offset:1024
	ds_read_b128 v[156:159], v160 offset:2048
	ds_read_b128 v[160:163], v160 offset:3072
	s_add_u32 s50, s82, 0xfff00080
	s_addc_u32 s56, s83, -1
	s_and_b64 s[34:35], s[84:85], exec
	s_cselect_b32 s87, s65, s56
	s_cselect_b32 s86, s69, s50
	s_cselect_b32 s85, s67, s88
	s_cselect_b32 s84, s77, s79
	s_add_i32 m0, s28, 0xc000
	ds_read_b128 v[164:167], v242
	ds_read_b128 v[168:171], v242 offset:1024
	ds_read_b128 v[172:175], v242 offset:2048
	ds_read_b128 v[176:179], v242 offset:3072
	ds_read_b128 v[180:183], v242 offset:4096
	ds_read_b128 v[184:187], v242 offset:5120
	ds_read_b128 v[188:191], v242 offset:6144
	ds_read_b128 v[226:229], v242 offset:7168
	global_load_lds_dwordx4 v220, s[82:83]
	s_add_i32 m0, s28, 0xe000
	s_nop 0
	global_load_lds_dwordx4 v222, s[82:83]
	s_waitcnt vmcnt(8)
	s_waitcnt lgkmcnt(0)
	s_setprio 1
	s_barrier
	v_mfma_f32_16x16x32_bf16 v[126:129], v[132:135], v[164:167], v[126:129]
	v_mfma_f32_16x16x32_bf16 v[126:129], v[136:139], v[168:171], v[126:129]
	v_mfma_f32_16x16x32_bf16 v[118:121], v[136:139], v[176:179], v[118:121]
	v_mfma_f32_16x16x32_bf16 v[118:121], v[132:135], v[172:175], v[118:121]
	v_mfma_f32_16x16x32_bf16 v[110:113], v[132:135], v[180:183], v[110:113]
	v_mfma_f32_16x16x32_bf16 v[110:113], v[136:139], v[184:187], v[110:113]
	v_mfma_f32_16x16x32_bf16 v[102:105], v[136:139], v[226:229], v[102:105]
	v_mfma_f32_16x16x32_bf16 v[102:105], v[132:135], v[188:191], v[102:105]
	v_mfma_f32_16x16x32_bf16 v[106:109], v[140:143], v[188:191], v[106:109]
	v_mfma_f32_16x16x32_bf16 v[106:109], v[144:147], v[226:229], v[106:109]
	v_mfma_f32_16x16x32_bf16 v[46:49], v[144:147], v[168:171], v[46:49]
	v_mfma_f32_16x16x32_bf16 v[46:49], v[140:143], v[164:167], v[46:49]
	v_mfma_f32_16x16x32_bf16 v[122:125], v[140:143], v[172:175], v[122:125]
	v_mfma_f32_16x16x32_bf16 v[122:125], v[144:147], v[176:179], v[122:125]
	v_mfma_f32_16x16x32_bf16 v[114:117], v[144:147], v[184:187], v[114:117]
	v_mfma_f32_16x16x32_bf16 v[114:117], v[140:143], v[180:183], v[114:117]
	s_setprio 0
	s_setprio 1
	v_mfma_f32_16x16x32_bf16 v[62:65], v[148:151], v[180:183], v[62:65]
	v_mfma_f32_16x16x32_bf16 v[62:65], v[152:155], v[184:187], v[62:65]
	v_mfma_f32_16x16x32_bf16 v[54:57], v[152:155], v[168:171], v[54:57]
	v_mfma_f32_16x16x32_bf16 v[54:57], v[148:151], v[164:167], v[54:57]
	v_mfma_f32_16x16x32_bf16 v[58:61], v[148:151], v[172:175], v[58:61]
	v_mfma_f32_16x16x32_bf16 v[58:61], v[152:155], v[176:179], v[58:61]
	v_mfma_f32_16x16x32_bf16 v[98:101], v[152:155], v[226:229], v[98:101]
	v_mfma_f32_16x16x32_bf16 v[98:101], v[148:151], v[188:191], v[98:101]
	v_mfma_f32_16x16x32_bf16 v[50:53], v[156:159], v[188:191], v[50:53]
	v_mfma_f32_16x16x32_bf16 v[50:53], v[160:163], v[226:229], v[50:53]
	v_mfma_f32_16x16x32_bf16 v[38:41], v[160:163], v[168:171], v[38:41]
	v_mfma_f32_16x16x32_bf16 v[38:41], v[156:159], v[164:167], v[38:41]
	v_mfma_f32_16x16x32_bf16 v[30:33], v[156:159], v[172:175], v[30:33]
	v_mfma_f32_16x16x32_bf16 v[30:33], v[160:163], v[176:179], v[30:33]
	v_mfma_f32_16x16x32_bf16 v[22:25], v[160:163], v[184:187], v[22:25]
	v_mfma_f32_16x16x32_bf16 v[22:25], v[156:159], v[180:183], v[22:25]
	s_barrier
	s_setprio 0
	s_add_i32 s34, s31, s45
	s_mov_b32 m0, s34
	ds_read_b128 v[164:167], v242 offset:16384
	ds_read_b128 v[168:171], v242 offset:17408
	ds_read_b128 v[172:175], v242 offset:18432
	ds_read_b128 v[176:179], v242 offset:19456
	ds_read_b128 v[180:183], v242 offset:20480
	ds_read_b128 v[184:187], v242 offset:21504
	ds_read_b128 v[188:191], v242 offset:22528
	ds_read_b128 v[226:229], v242 offset:23552
	global_load_lds_dwordx4 v208, s[84:85]
	s_add_i32 m0, s34, 0x2000
	s_add_u32 s34, s84, 0x100000
	s_addc_u32 s35, s85, 0
	s_add_i32 s50, s52, s45
	global_load_lds_dwordx4 v212, s[84:85]
	s_mov_b32 m0, s50
	s_nop 0
	global_load_lds_dwordx4 v208, s[34:35]
	s_add_i32 m0, s50, 0x2000
	s_nop 0
	global_load_lds_dwordx4 v212, s[34:35]
	s_mov_b32 m0, s28
	s_nop 0
	global_load_lds_dwordx4 v206, s[86:87]
	s_mov_b32 m0, s29
	s_nop 0
	global_load_lds_dwordx4 v210, s[86:87]
	s_waitcnt vmcnt(8)
	s_waitcnt lgkmcnt(0)
	s_setprio 1
	s_barrier
	v_mfma_f32_16x16x32_bf16 v[78:81], v[132:135], v[164:167], v[78:81]
	v_mfma_f32_16x16x32_bf16 v[78:81], v[136:139], v[168:171], v[78:81]
	v_mfma_f32_16x16x32_bf16 v[66:69], v[136:139], v[176:179], v[66:69]
	v_mfma_f32_16x16x32_bf16 v[66:69], v[132:135], v[172:175], v[66:69]
	v_mfma_f32_16x16x32_bf16 v[70:73], v[132:135], v[180:183], v[70:73]
	v_mfma_f32_16x16x32_bf16 v[70:73], v[136:139], v[184:187], v[70:73]
	v_mfma_f32_16x16x32_bf16 v[74:77], v[136:139], v[226:229], v[74:77]
	v_mfma_f32_16x16x32_bf16 v[74:77], v[132:135], v[188:191], v[74:77]
	v_mfma_f32_16x16x32_bf16 v[10:13], v[140:143], v[188:191], v[10:13]
	v_mfma_f32_16x16x32_bf16 v[10:13], v[144:147], v[226:229], v[10:13]
	v_mfma_f32_16x16x32_bf16 v[14:17], v[144:147], v[168:171], v[14:17]
	v_mfma_f32_16x16x32_bf16 v[14:17], v[140:143], v[164:167], v[14:17]
	v_mfma_f32_16x16x32_bf16 v[94:97], v[140:143], v[172:175], v[94:97]
	v_mfma_f32_16x16x32_bf16 v[94:97], v[144:147], v[176:179], v[94:97]
	v_mfma_f32_16x16x32_bf16 v[90:93], v[144:147], v[184:187], v[90:93]
	v_mfma_f32_16x16x32_bf16 v[90:93], v[140:143], v[180:183], v[90:93]
	s_setprio 0
	s_setprio 1
	v_mfma_f32_16x16x32_bf16 v[86:89], v[148:151], v[180:183], v[86:89]
	v_mfma_f32_16x16x32_bf16 v[86:89], v[152:155], v[184:187], v[86:89]
	v_mfma_f32_16x16x32_bf16 v[42:45], v[152:155], v[168:171], v[42:45]
	v_mfma_f32_16x16x32_bf16 v[42:45], v[148:151], v[164:167], v[42:45]
	v_mfma_f32_16x16x32_bf16 v[34:37], v[148:151], v[172:175], v[34:37]
	v_mfma_f32_16x16x32_bf16 v[34:37], v[152:155], v[176:179], v[34:37]
	v_mfma_f32_16x16x32_bf16 v[82:85], v[152:155], v[226:229], v[82:85]
	v_mfma_f32_16x16x32_bf16 v[82:85], v[148:151], v[188:191], v[82:85]
	v_mfma_f32_16x16x32_bf16 v[18:21], v[156:159], v[188:191], v[18:21]
	v_mfma_f32_16x16x32_bf16 v[18:21], v[160:163], v[226:229], v[18:21]
	v_mfma_f32_16x16x32_bf16 v[2:5], v[160:163], v[168:171], v[2:5]
	v_mfma_f32_16x16x32_bf16 v[2:5], v[156:159], v[164:167], v[2:5]
	v_mfma_f32_16x16x32_bf16 v[6:9], v[156:159], v[172:175], v[6:9]
	v_mfma_f32_16x16x32_bf16 v[6:9], v[160:163], v[176:179], v[6:9]
	v_mfma_f32_16x16x32_bf16 v[26:29], v[160:163], v[184:187], v[26:29]
	v_mfma_f32_16x16x32_bf16 v[26:29], v[156:159], v[180:183], v[26:29]
	s_barrier
; #define PG8_STAGE(bufoff, gbase, voff) do { _Pragma("unroll") for (int _i = 0; _i < 2; ++_i) \
;         __builtin_amdgcn_global_load_lds((const unsigned*)((const char*)(gbase) + (voff)[_i]), (PG8_LAS unsigned*)(lds + (bufoff) + ldsw + _i * 8192), 16, 0, 0); } while (0)
; #define PG8_LDA(dst, b, h) do { _Pragma("unroll") for (int m = 0; m < 4; ++m) _Pragma("unroll") for (int k = 0; k < 2; ++k) dst[m][k] = *(const PG8_LAS bf16x8*)(lds + PG8_SA(b, h) + aoff + m * 2048 + k * 1024); } while (0)
; #define PG8_LDB(dst, b, h) do { _Pragma("unroll") for (int n = 0; n < 2; ++n) _Pragma("unroll") for (int k = 0; k < 2; ++k) dst[n][k] = *(const PG8_LAS bf16x8*)(lds + PG8_SB(b, h) + boff + n * 2048 + k * 1024); } while (0)
; #define PG8_MMA(ai, bj, At, Bt) do { __builtin_amdgcn_s_setprio(1); _Pragma("unroll") for (int m = 0; m < 4; ++m) _Pragma("unroll") for (int n = 0; n < 2; ++n) _Pragma("unroll") for (int k = 0; k < 2; ++k) \
;         acc[ai][bj][m][n] = __builtin_amdgcn_mfma_f32_16x16x32_bf16(Bt[n][k], At[m][k], acc[ai][bj][m][n], 0, 0, 0); __builtin_amdgcn_s_setprio(0); } while (0)
; #define PG8_WAIT_V(n) asm volatile("s_waitcnt vmcnt(" #n ")" ::: "memory")
; #define PG8_WAIT_L(n) asm volatile("s_waitcnt lgkmcnt(" #n ")" ::: "memory")
; #define PG8_BAR __builtin_amdgcn_s_barrier()
; #define PG8_SCHED __builtin_amdgcn_sched_barrier(0)
; template <class Epi, class Sched, bool ALIGN_EPI = false, bool SP2 = false>
; __device__ __forceinline__ void gemm_phase(PG8_LAS unsigned char* lds, const Gemm g, const Sched& S, const Epi& E) {
;     ...
;         for (int t = 0; t < nt; t += 2) {
;     ...
;             PG8_LDB(B0, 1, 0); PG8_LDB(B1, 1, 1); PG8_SCHED; PG8_LDA(At, 1, 0); PG8_STAGE(PG8_SA(0, 1), a2 + hstep, voffA);
;             PG8_WAIT_V(8); PG8_WAIT_L(0); PG8_BAR; PG8_MMA(0, 0, At, B0); PG8_MMA(0, 1, At, B1); PG8_BAR; PG8_SCHED;
;             PG8_LDA(At, 1, 1); PG8_STAGE(PG8_SB(1, 0), b3, voffB); PG8_STAGE(PG8_SB(1, 1), b3 + hstep, voffB); PG8_STAGE(PG8_SA(1, 0), a3, voffA);
;             PG8_WAIT_V(8); PG8_WAIT_L(0); PG8_BAR; PG8_MMA(1, 0, At, B0); PG8_MMA(1, 1, At, B1); PG8_BAR; PG8_SCHED;
	s_setprio 0
	s_add_i32 s50, 0, 0x18000
	s_add_i32 s56, 0, 0x1c000
	v_add_u32_e32 v144, s50, v201
	v_add_u32_e32 v160, s56, v201
	ds_read_b128 v[132:135], v144
	ds_read_b128 v[136:139], v144 offset:1024
	ds_read_b128 v[140:143], v144 offset:2048
	ds_read_b128 v[144:147], v144 offset:3072
	ds_read_b128 v[148:151], v160
	ds_read_b128 v[152:155], v160 offset:1024
	ds_read_b128 v[156:159], v160 offset:2048
	ds_read_b128 v[160:163], v160 offset:3072
	s_add_u32 s34, s86, 0x100000
	s_addc_u32 s35, s87, 0
	s_mov_b32 m0, s16
	ds_read_b128 v[164:167], v242 offset:32768
	ds_read_b128 v[168:171], v242 offset:33792
	ds_read_b128 v[172:175], v242 offset:34816
	ds_read_b128 v[176:179], v242 offset:35840
	ds_read_b128 v[180:183], v242 offset:36864
	ds_read_b128 v[184:187], v242 offset:37888
	ds_read_b128 v[188:191], v242 offset:38912
	ds_read_b128 v[226:229], v242 offset:39936
	global_load_lds_dwordx4 v206, s[34:35]
	s_mov_b32 m0, s17
	s_nop 0
	global_load_lds_dwordx4 v210, s[34:35]
	s_waitcnt vmcnt(8)
	s_waitcnt lgkmcnt(0)
	s_setprio 1
	s_barrier
	v_mfma_f32_16x16x32_bf16 v[126:129], v[132:135], v[164:167], v[126:129]
	v_mfma_f32_16x16x32_bf16 v[126:129], v[136:139], v[168:171], v[126:129]
	v_mfma_f32_16x16x32_bf16 v[118:121], v[136:139], v[176:179], v[118:121]
	v_mfma_f32_16x16x32_bf16 v[118:121], v[132:135], v[172:175], v[118:121]
	v_mfma_f32_16x16x32_bf16 v[110:113], v[132:135], v[180:183], v[110:113]
	v_mfma_f32_16x16x32_bf16 v[110:113], v[136:139], v[184:187], v[110:113]
	v_mfma_f32_16x16x32_bf16 v[102:105], v[136:139], v[226:229], v[102:105]
	v_mfma_f32_16x16x32_bf16 v[102:105], v[132:135], v[188:191], v[102:105]
	v_mfma_f32_16x16x32_bf16 v[106:109], v[140:143], v[188:191], v[106:109]
	v_mfma_f32_16x16x32_bf16 v[106:109], v[144:147], v[226:229], v[106:109]
	v_mfma_f32_16x16x32_bf16 v[46:49], v[144:147], v[168:171], v[46:49]
	v_mfma_f32_16x16x32_bf16 v[46:49], v[140:143], v[164:167], v[46:49]
	v_mfma_f32_16x16x32_bf16 v[122:125], v[140:143], v[172:175], v[122:125]
	v_mfma_f32_16x16x32_bf16 v[122:125], v[144:147], v[176:179], v[122:125]
	v_mfma_f32_16x16x32_bf16 v[114:117], v[144:147], v[184:187], v[114:117]
	v_mfma_f32_16x16x32_bf16 v[114:117], v[140:143], v[180:183], v[114:117]
	s_setprio 0
	s_setprio 1
	v_mfma_f32_16x16x32_bf16 v[62:65], v[148:151], v[180:183], v[62:65]
	v_mfma_f32_16x16x32_bf16 v[62:65], v[152:155], v[184:187], v[62:65]
	v_mfma_f32_16x16x32_bf16 v[54:57], v[152:155], v[168:171], v[54:57]
	v_mfma_f32_16x16x32_bf16 v[54:57], v[148:151], v[164:167], v[54:57]
	v_mfma_f32_16x16x32_bf16 v[58:61], v[148:151], v[172:175], v[58:61]
	v_mfma_f32_16x16x32_bf16 v[58:61], v[152:155], v[176:179], v[58:61]
	v_mfma_f32_16x16x32_bf16 v[98:101], v[152:155], v[226:229], v[98:101]
	v_mfma_f32_16x16x32_bf16 v[98:101], v[148:151], v[188:191], v[98:101]
	v_mfma_f32_16x16x32_bf16 v[50:53], v[156:159], v[188:191], v[50:53]
	v_mfma_f32_16x16x32_bf16 v[50:53], v[160:163], v[226:229], v[50:53]
	v_mfma_f32_16x16x32_bf16 v[38:41], v[160:163], v[168:171], v[38:41]
	v_mfma_f32_16x16x32_bf16 v[38:41], v[156:159], v[164:167], v[38:41]
	v_mfma_f32_16x16x32_bf16 v[30:33], v[156:159], v[172:175], v[30:33]
	v_mfma_f32_16x16x32_bf16 v[30:33], v[160:163], v[176:179], v[30:33]
	v_mfma_f32_16x16x32_bf16 v[22:25], v[160:163], v[184:187], v[22:25]
	v_mfma_f32_16x16x32_bf16 v[22:25], v[156:159], v[180:183], v[22:25]
	s_barrier
	s_setprio 0
	s_add_i32 s34, s50, s45
	s_add_u32 s98, s84, s54
	s_addc_u32 s99, s85, s55
	s_mov_b32 m0, s34
	ds_read_b128 v[164:167], v242 offset:49152
	ds_read_b128 v[168:171], v242 offset:50176
	ds_read_b128 v[172:175], v242 offset:51200
	ds_read_b128 v[176:179], v242 offset:52224
	ds_read_b128 v[180:183], v242 offset:53248
	ds_read_b128 v[184:187], v242 offset:54272
	ds_read_b128 v[188:191], v242 offset:55296
	ds_read_b128 v[226:229], v242 offset:56320
	global_load_lds_dwordx4 v208, s[98:99]
	s_add_i32 m0, s34, 0x2000
	s_add_u32 s34, s84, 0x100080
	s_addc_u32 s35, s85, 0
	s_add_i32 s50, s56, s45
	global_load_lds_dwordx4 v212, s[98:99]
	s_mov_b32 m0, s50
	s_nop 0
	global_load_lds_dwordx4 v208, s[34:35]
	s_add_i32 m0, s50, 0x2000
	s_nop 0
	global_load_lds_dwordx4 v212, s[34:35]
	s_add_u32 s100, s86, s54
	s_addc_u32 s101, s87, s55
	s_mov_b32 m0, s39
	s_nop 0
	global_load_lds_dwordx4 v206, s[100:101]
	s_mov_b32 m0, s46
	s_nop 0
	global_load_lds_dwordx4 v210, s[100:101]
	s_waitcnt vmcnt(8)
	s_waitcnt lgkmcnt(0)
	s_setprio 1
	s_barrier
	v_mfma_f32_16x16x32_bf16 v[78:81], v[132:135], v[164:167], v[78:81]
	v_mfma_f32_16x16x32_bf16 v[78:81], v[136:139], v[168:171], v[78:81]
	v_mfma_f32_16x16x32_bf16 v[66:69], v[136:139], v[176:179], v[66:69]
	v_mfma_f32_16x16x32_bf16 v[66:69], v[132:135], v[172:175], v[66:69]
	v_mfma_f32_16x16x32_bf16 v[70:73], v[132:135], v[180:183], v[70:73]
	v_mfma_f32_16x16x32_bf16 v[70:73], v[136:139], v[184:187], v[70:73]
	v_mfma_f32_16x16x32_bf16 v[74:77], v[136:139], v[226:229], v[74:77]
	v_mfma_f32_16x16x32_bf16 v[74:77], v[132:135], v[188:191], v[74:77]
	v_mfma_f32_16x16x32_bf16 v[10:13], v[140:143], v[188:191], v[10:13]
	v_mfma_f32_16x16x32_bf16 v[10:13], v[144:147], v[226:229], v[10:13]
	v_mfma_f32_16x16x32_bf16 v[14:17], v[144:147], v[168:171], v[14:17]
	v_mfma_f32_16x16x32_bf16 v[14:17], v[140:143], v[164:167], v[14:17]
	v_mfma_f32_16x16x32_bf16 v[94:97], v[140:143], v[172:175], v[94:97]
	v_mfma_f32_16x16x32_bf16 v[94:97], v[144:147], v[176:179], v[94:97]
	v_mfma_f32_16x16x32_bf16 v[90:93], v[144:147], v[184:187], v[90:93]
	v_mfma_f32_16x16x32_bf16 v[90:93], v[140:143], v[180:183], v[90:93]
	s_setprio 0
	s_setprio 1
	v_mfma_f32_16x16x32_bf16 v[86:89], v[148:151], v[180:183], v[86:89]
	v_mfma_f32_16x16x32_bf16 v[86:89], v[152:155], v[184:187], v[86:89]
	v_mfma_f32_16x16x32_bf16 v[42:45], v[152:155], v[168:171], v[42:45]
	v_mfma_f32_16x16x32_bf16 v[42:45], v[148:151], v[164:167], v[42:45]
	v_mfma_f32_16x16x32_bf16 v[34:37], v[148:151], v[172:175], v[34:37]
	v_mfma_f32_16x16x32_bf16 v[34:37], v[152:155], v[176:179], v[34:37]
	v_mfma_f32_16x16x32_bf16 v[82:85], v[152:155], v[226:229], v[82:85]
	v_mfma_f32_16x16x32_bf16 v[82:85], v[148:151], v[188:191], v[82:85]
	v_mfma_f32_16x16x32_bf16 v[18:21], v[156:159], v[188:191], v[18:21]
	v_mfma_f32_16x16x32_bf16 v[18:21], v[160:163], v[226:229], v[18:21]
	v_mfma_f32_16x16x32_bf16 v[2:5], v[160:163], v[168:171], v[2:5]
	v_mfma_f32_16x16x32_bf16 v[2:5], v[156:159], v[164:167], v[2:5]
	v_mfma_f32_16x16x32_bf16 v[6:9], v[156:159], v[172:175], v[6:9]
	v_mfma_f32_16x16x32_bf16 v[6:9], v[160:163], v[176:179], v[6:9]
	v_mfma_f32_16x16x32_bf16 v[26:29], v[160:163], v[184:187], v[26:29]
	v_mfma_f32_16x16x32_bf16 v[26:29], v[156:159], v[180:183], v[26:29]
	s_barrier
	s_setprio 0
	s_add_i32 s89, s89, 2
	s_add_u32 s82, s82, 0x100
	s_addc_u32 s83, s83, 0
	s_add_u32 s79, s79, 0x100
	s_addc_u32 s88, s88, 0
	s_cmp_gt_u32 s89, 61
	s_cbranch_scc1 .LBB0_1490

; #define PG8_STAGE(bufoff, gbase, voff) do { _Pragma("unroll") for (int _i = 0; _i < 2; ++_i) \
;         __builtin_amdgcn_global_load_lds((const unsigned*)((const char*)(gbase) + (voff)[_i]), (PG8_LAS unsigned*)(lds + (bufoff) + ldsw + _i * 8192), 16, 0, 0); } while (0)
; #define PG8_LDA(dst, b, h) do { _Pragma("unroll") for (int m = 0; m < 4; ++m) _Pragma("unroll") for (int k = 0; k < 2; ++k) dst[m][k] = *(const PG8_LAS bf16x8*)(lds + PG8_SA(b, h) + aoff + m * 2048 + k * 1024); } while (0)
; #define PG8_LDB(dst, b, h) do { _Pragma("unroll") for (int n = 0; n < 2; ++n) _Pragma("unroll") for (int k = 0; k < 2; ++k) dst[n][k] = *(const PG8_LAS bf16x8*)(lds + PG8_SB(b, h) + boff + n * 2048 + k * 1024); } while (0)
; #define PG8_MMA(ai, bj, At, Bt) do { __builtin_amdgcn_s_setprio(1); _Pragma("unroll") for (int m = 0; m < 4; ++m) _Pragma("unroll") for (int n = 0; n < 2; ++n) _Pragma("unroll") for (int k = 0; k < 2; ++k) \
;         acc[ai][bj][m][n] = __builtin_amdgcn_mfma_f32_16x16x32_bf16(Bt[n][k], At[m][k], acc[ai][bj][m][n], 0, 0, 0); __builtin_amdgcn_s_setprio(0); } while (0)
; #define PG8_WAIT_V(n) asm volatile("s_waitcnt vmcnt(" #n ")" ::: "memory")
; #define PG8_WAIT_L(n) asm volatile("s_waitcnt lgkmcnt(" #n ")" ::: "memory")
; #define PG8_BAR __builtin_amdgcn_s_barrier()
; #define PG8_SCHED __builtin_amdgcn_sched_barrier(0)
; template <class Epi, class Sched, bool ALIGN_EPI = false, bool SP2 = false>
; __device__ __forceinline__ void gemm_phase(PG8_LAS unsigned char* lds, const Gemm g, const Sched& S, const Epi& E) {
;     ...
;             PG8_LDB(B0, 0, 0); PG8_LDB(B1, 0, 1); PG8_SCHED; PG8_LDA(At, 0, 0); PG8_STAGE(PG8_SA(1, 1), a1 + hstep, voffA);
;             PG8_WAIT_V(8); PG8_WAIT_L(0); PG8_BAR; PG8_MMA(0, 0, At, B0); PG8_MMA(0, 1, At, B1); PG8_BAR; PG8_SCHED;
;     ...
;         for (int a = 0; a < 2; ++a)
; #pragma unroll
;             for (int b = 0; b < 2; ++b)
; #pragma unroll
;                 for (int m = 0; m < 4; ++m)
; #pragma unroll
;                     for (int n = 0; n < 2; ++n) acc[a][b][m][n] = (f32x4){0.f, 0.f, 0.f, 0.f};
.LBB0_1730:
	s_add_u32 s54, s48, 0x100
	v_mov_b32_e32 v2, 0
	s_addc_u32 s55, s49, 0
	s_mov_b32 s56, -2
	v_mov_b64_e32 v[2:3], 0
	v_mov_b64_e32 v[4:5], 0
	v_mov_b64_e32 v[6:7], 0
	v_mov_b64_e32 v[8:9], 0
	v_mov_b64_e32 v[10:11], 0
	v_mov_b64_e32 v[12:13], 0
	v_mov_b64_e32 v[14:15], 0
	v_mov_b64_e32 v[16:17], 0
	v_mov_b64_e32 v[18:19], 0
	v_mov_b64_e32 v[20:21], 0
	v_mov_b64_e32 v[22:23], 0
	v_mov_b64_e32 v[24:25], 0
	v_mov_b64_e32 v[26:27], 0
	v_mov_b64_e32 v[28:29], 0
	v_mov_b64_e32 v[30:31], 0
	v_mov_b64_e32 v[32:33], 0
	v_mov_b64_e32 v[34:35], 0
	v_mov_b64_e32 v[36:37], 0
	v_mov_b64_e32 v[38:39], 0
	v_mov_b64_e32 v[40:41], 0
	v_mov_b64_e32 v[42:43], 0
	v_mov_b64_e32 v[44:45], 0
	v_mov_b64_e32 v[46:47], 0
	v_mov_b64_e32 v[48:49], 0
	v_mov_b64_e32 v[50:51], 0
	v_mov_b64_e32 v[52:53], 0
	v_mov_b64_e32 v[54:55], 0
	v_mov_b64_e32 v[56:57], 0
	v_mov_b64_e32 v[58:59], 0
	v_mov_b64_e32 v[60:61], 0
	v_mov_b64_e32 v[62:63], 0
	v_mov_b64_e32 v[64:65], 0
	v_mov_b64_e32 v[66:67], 0
	v_mov_b64_e32 v[68:69], 0
	v_mov_b64_e32 v[70:71], 0
	v_mov_b64_e32 v[72:73], 0
	v_mov_b64_e32 v[74:75], 0
	v_mov_b64_e32 v[76:77], 0
	v_mov_b64_e32 v[78:79], 0
	v_mov_b64_e32 v[80:81], 0
	v_mov_b64_e32 v[82:83], 0
	v_mov_b64_e32 v[84:85], 0
	v_mov_b64_e32 v[86:87], 0
	v_mov_b64_e32 v[88:89], 0
	v_mov_b64_e32 v[90:91], 0
	v_mov_b64_e32 v[92:93], 0
	v_mov_b64_e32 v[94:95], 0
	v_mov_b64_e32 v[96:97], 0
	v_mov_b64_e32 v[98:99], 0
	v_mov_b64_e32 v[100:101], 0
	v_mov_b64_e32 v[102:103], 0
	v_mov_b64_e32 v[104:105], 0
	v_mov_b64_e32 v[106:107], 0
	v_mov_b64_e32 v[108:109], 0
	v_mov_b64_e32 v[110:111], 0
	v_mov_b64_e32 v[112:113], 0
	v_mov_b64_e32 v[114:115], 0
	v_mov_b64_e32 v[116:117], 0
	v_mov_b64_e32 v[118:119], 0
	v_mov_b64_e32 v[120:121], 0
	v_mov_b64_e32 v[122:123], 0
	v_mov_b64_e32 v[124:125], 0
	v_mov_b64_e32 v[126:127], 0
	v_mov_b64_e32 v[128:129], 0
.LBB0_1731:
	ds_read_b128 v[170:173], v166
	ds_read_b128 v[174:177], v166 offset:1024
	ds_read_b128 v[178:181], v166 offset:2048
	ds_read_b128 v[182:185], v166 offset:3072
	ds_read_b128 v[186:189], v167
	ds_read_b128 v[190:193], v167 offset:1024
	ds_read_b128 v[196:199], v167 offset:2048
	ds_read_b128 v[202:205], v167 offset:3072
	s_add_u32 s48, s40, 0x100
	s_addc_u32 s49, s41, 0
	s_cmpk_eq_i32 s56, 0xa8
	s_cselect_b32 s53, s7, s49
	s_cselect_b32 s52, s6, s48
	s_cselect_b32 s51, s39, s55
	s_cselect_b32 s50, s38, s54
	v_lshl_add_u64 v[146:147], s[40:41], 0, v[138:139]
	s_add_i32 m0, s16, 0xc000
	ds_read_b128 v[206:209], v168
	ds_read_b128 v[210:213], v168 offset:1024
	ds_read_b128 v[214:217], v168 offset:2048
	ds_read_b128 v[218:221], v168 offset:3072
	ds_read_b128 v[222:225], v168 offset:4096
	ds_read_b128 v[226:229], v168 offset:5120
	ds_read_b128 v[230:233], v168 offset:6144
	ds_read_b128 v[234:237], v168 offset:7168
	global_load_lds_dwordx4 v[146:147], off
	v_lshl_add_u64 v[146:147], s[40:41], 0, v[140:141]
	s_add_i32 m0, s16, 0xe000
	s_nop 0
	global_load_lds_dwordx4 v[146:147], off
	s_waitcnt vmcnt(8)
	s_waitcnt lgkmcnt(0)
	s_setprio 1
	s_barrier
	v_mfma_f32_16x16x32_bf16 v[126:129], v[170:173], v[206:209], v[126:129]
	v_mfma_f32_16x16x32_bf16 v[126:129], v[174:177], v[210:213], v[126:129]
	v_mfma_f32_16x16x32_bf16 v[110:113], v[174:177], v[218:221], v[110:113]
	v_mfma_f32_16x16x32_bf16 v[110:113], v[170:173], v[214:217], v[110:113]
	v_mfma_f32_16x16x32_bf16 v[94:97], v[170:173], v[222:225], v[94:97]
	v_mfma_f32_16x16x32_bf16 v[94:97], v[174:177], v[226:229], v[94:97]
	v_mfma_f32_16x16x32_bf16 v[78:81], v[174:177], v[234:237], v[78:81]
	v_mfma_f32_16x16x32_bf16 v[78:81], v[170:173], v[230:233], v[78:81]
	v_mfma_f32_16x16x32_bf16 v[74:77], v[178:181], v[230:233], v[74:77]
	v_mfma_f32_16x16x32_bf16 v[74:77], v[182:185], v[234:237], v[74:77]
	v_mfma_f32_16x16x32_bf16 v[122:125], v[182:185], v[210:213], v[122:125]
	v_mfma_f32_16x16x32_bf16 v[122:125], v[178:181], v[206:209], v[122:125]
	v_mfma_f32_16x16x32_bf16 v[106:109], v[178:181], v[214:217], v[106:109]
	v_mfma_f32_16x16x32_bf16 v[106:109], v[182:185], v[218:221], v[106:109]
	v_mfma_f32_16x16x32_bf16 v[90:93], v[182:185], v[226:229], v[90:93]
	v_mfma_f32_16x16x32_bf16 v[90:93], v[178:181], v[222:225], v[90:93]
	s_setprio 0
	s_setprio 1
	v_mfma_f32_16x16x32_bf16 v[86:89], v[186:189], v[222:225], v[86:89]
	v_mfma_f32_16x16x32_bf16 v[86:89], v[190:193], v[226:229], v[86:89]
	v_mfma_f32_16x16x32_bf16 v[118:121], v[190:193], v[210:213], v[118:121]
	v_mfma_f32_16x16x32_bf16 v[118:121], v[186:189], v[206:209], v[118:121]
	v_mfma_f32_16x16x32_bf16 v[102:105], v[186:189], v[214:217], v[102:105]
	v_mfma_f32_16x16x32_bf16 v[102:105], v[190:193], v[218:221], v[102:105]
	v_mfma_f32_16x16x32_bf16 v[70:73], v[190:193], v[234:237], v[70:73]
	v_mfma_f32_16x16x32_bf16 v[70:73], v[186:189], v[230:233], v[70:73]
	v_mfma_f32_16x16x32_bf16 v[66:69], v[196:199], v[230:233], v[66:69]
	v_mfma_f32_16x16x32_bf16 v[66:69], v[202:205], v[234:237], v[66:69]
	v_mfma_f32_16x16x32_bf16 v[114:117], v[202:205], v[210:213], v[114:117]
	v_mfma_f32_16x16x32_bf16 v[114:117], v[196:199], v[206:209], v[114:117]
	v_mfma_f32_16x16x32_bf16 v[98:101], v[196:199], v[214:217], v[98:101]
	v_mfma_f32_16x16x32_bf16 v[98:101], v[202:205], v[218:221], v[98:101]
	v_mfma_f32_16x16x32_bf16 v[82:85], v[202:205], v[226:229], v[82:85]
	v_mfma_f32_16x16x32_bf16 v[82:85], v[196:199], v[222:225], v[82:85]
	s_barrier
; #define PG8_STAGE(bufoff, gbase, voff) do { _Pragma("unroll") for (int _i = 0; _i < 2; ++_i) \
;         __builtin_amdgcn_global_load_lds((const unsigned*)((const char*)(gbase) + (voff)[_i]), (PG8_LAS unsigned*)(lds + (bufoff) + ldsw + _i * 8192), 16, 0, 0); } while (0)
; #define PG8_LDA(dst, b, h) do { _Pragma("unroll") for (int m = 0; m < 4; ++m) _Pragma("unroll") for (int k = 0; k < 2; ++k) dst[m][k] = *(const PG8_LAS bf16x8*)(lds + PG8_SA(b, h) + aoff + m * 2048 + k * 1024); } while (0)
; #define PG8_LDB(dst, b, h) do { _Pragma("unroll") for (int n = 0; n < 2; ++n) _Pragma("unroll") for (int k = 0; k < 2; ++k) dst[n][k] = *(const PG8_LAS bf16x8*)(lds + PG8_SB(b, h) + boff + n * 2048 + k * 1024); } while (0)
; #define PG8_MMA(ai, bj, At, Bt) do { __builtin_amdgcn_s_setprio(1); _Pragma("unroll") for (int m = 0; m < 4; ++m) _Pragma("unroll") for (int n = 0; n < 2; ++n) _Pragma("unroll") for (int k = 0; k < 2; ++k) \
;         acc[ai][bj][m][n] = __builtin_amdgcn_mfma_f32_16x16x32_bf16(Bt[n][k], At[m][k], acc[ai][bj][m][n], 0, 0, 0); __builtin_amdgcn_s_setprio(0); } while (0)
; #define PG8_WAIT_V(n) asm volatile("s_waitcnt vmcnt(" #n ")" ::: "memory")
; #define PG8_WAIT_L(n) asm volatile("s_waitcnt lgkmcnt(" #n ")" ::: "memory")
; #define PG8_BAR __builtin_amdgcn_s_barrier()
; #define PG8_SCHED __builtin_amdgcn_sched_barrier(0)
; template <class Epi, class Sched, bool ALIGN_EPI = false, bool SP2 = false>
; __device__ __forceinline__ void gemm_phase(PG8_LAS unsigned char* lds, const Gemm g, const Sched& S, const Epi& E) {
;     ...
;             PG8_LDA(At, 0, 1); PG8_STAGE(PG8_SB(0, 0), b2, voffB); PG8_STAGE(PG8_SB(0, 1), b2 + hstep, voffB); PG8_STAGE(PG8_SA(0, 0), a2, voffA);
;             PG8_WAIT_V(8); PG8_WAIT_L(0); PG8_BAR; PG8_MMA(1, 0, At, B0); PG8_MMA(1, 1, At, B1); PG8_BAR; PG8_SCHED;
;             PG8_LDB(B0, 1, 0); PG8_LDB(B1, 1, 1); PG8_SCHED; PG8_LDA(At, 1, 0); PG8_STAGE(PG8_SA(0, 1), a2 + hstep, voffA);
	s_setprio 0
	s_add_i32 s40, s31, s3
	s_mov_b32 m0, s40
	ds_read_b128 v[206:209], v168 offset:16384
	ds_read_b128 v[210:213], v168 offset:17408
	ds_read_b128 v[214:217], v168 offset:18432
	ds_read_b128 v[218:221], v168 offset:19456
	ds_read_b128 v[222:225], v168 offset:20480
	ds_read_b128 v[226:229], v168 offset:21504
	ds_read_b128 v[230:233], v168 offset:22528
	ds_read_b128 v[234:237], v168 offset:23552
	global_load_lds_dwordx4 v132, s[50:51]
	s_add_i32 m0, s40, 0x2000
	s_add_u32 s40, s50, 0x2b0000
	s_addc_u32 s41, s51, 0
	s_add_i32 s57, s35, s3
	global_load_lds_dwordx4 v136, s[50:51]
	s_mov_b32 m0, s57
	s_nop 0
	global_load_lds_dwordx4 v132, s[40:41]
	s_add_i32 m0, s57, 0x2000
	s_nop 0
	global_load_lds_dwordx4 v136, s[40:41]
	s_mov_b32 m0, s16
	s_nop 0
	global_load_lds_dwordx4 v130, s[52:53]
	s_mov_b32 m0, s17
	s_nop 0
	global_load_lds_dwordx4 v134, s[52:53]
	s_waitcnt vmcnt(8)
	s_waitcnt lgkmcnt(0)
	s_setprio 1
	s_barrier
	v_mfma_f32_16x16x32_bf16 v[62:65], v[170:173], v[206:209], v[62:65]
	v_mfma_f32_16x16x32_bf16 v[62:65], v[174:177], v[210:213], v[62:65]
	v_mfma_f32_16x16x32_bf16 v[46:49], v[174:177], v[218:221], v[46:49]
	v_mfma_f32_16x16x32_bf16 v[46:49], v[170:173], v[214:217], v[46:49]
	v_mfma_f32_16x16x32_bf16 v[30:33], v[170:173], v[222:225], v[30:33]
	v_mfma_f32_16x16x32_bf16 v[30:33], v[174:177], v[226:229], v[30:33]
	v_mfma_f32_16x16x32_bf16 v[14:17], v[174:177], v[234:237], v[14:17]
	v_mfma_f32_16x16x32_bf16 v[14:17], v[170:173], v[230:233], v[14:17]
	v_mfma_f32_16x16x32_bf16 v[10:13], v[178:181], v[230:233], v[10:13]
	v_mfma_f32_16x16x32_bf16 v[10:13], v[182:185], v[234:237], v[10:13]
	v_mfma_f32_16x16x32_bf16 v[58:61], v[182:185], v[210:213], v[58:61]
	v_mfma_f32_16x16x32_bf16 v[58:61], v[178:181], v[206:209], v[58:61]
	v_mfma_f32_16x16x32_bf16 v[42:45], v[178:181], v[214:217], v[42:45]
	v_mfma_f32_16x16x32_bf16 v[42:45], v[182:185], v[218:221], v[42:45]
	v_mfma_f32_16x16x32_bf16 v[26:29], v[182:185], v[226:229], v[26:29]
	v_mfma_f32_16x16x32_bf16 v[26:29], v[178:181], v[222:225], v[26:29]
	s_setprio 0
	s_setprio 1
	v_mfma_f32_16x16x32_bf16 v[22:25], v[186:189], v[222:225], v[22:25]
	v_mfma_f32_16x16x32_bf16 v[22:25], v[190:193], v[226:229], v[22:25]
	v_mfma_f32_16x16x32_bf16 v[54:57], v[190:193], v[210:213], v[54:57]
	v_mfma_f32_16x16x32_bf16 v[54:57], v[186:189], v[206:209], v[54:57]
	v_mfma_f32_16x16x32_bf16 v[38:41], v[186:189], v[214:217], v[38:41]
	v_mfma_f32_16x16x32_bf16 v[38:41], v[190:193], v[218:221], v[38:41]
	v_mfma_f32_16x16x32_bf16 v[6:9], v[190:193], v[234:237], v[6:9]
	v_mfma_f32_16x16x32_bf16 v[6:9], v[186:189], v[230:233], v[6:9]
	v_mfma_f32_16x16x32_bf16 v[2:5], v[196:199], v[230:233], v[2:5]
	v_mfma_f32_16x16x32_bf16 v[2:5], v[202:205], v[234:237], v[2:5]
	v_mfma_f32_16x16x32_bf16 v[50:53], v[202:205], v[210:213], v[50:53]
	v_mfma_f32_16x16x32_bf16 v[50:53], v[196:199], v[206:209], v[50:53]
	v_mfma_f32_16x16x32_bf16 v[34:37], v[196:199], v[214:217], v[34:37]
	v_mfma_f32_16x16x32_bf16 v[34:37], v[202:205], v[218:221], v[34:37]
	v_mfma_f32_16x16x32_bf16 v[18:21], v[202:205], v[226:229], v[18:21]
	v_mfma_f32_16x16x32_bf16 v[18:21], v[196:199], v[222:225], v[18:21]
	s_barrier
	s_setprio 0
	s_add_i32 s57, 0, 0x18000
	v_add_u32_e32 v169, s57, v148
	s_add_i32 s58, 0, 0x1c000
	ds_read_b128 v[170:173], v169
	ds_read_b128 v[174:177], v169 offset:1024
	ds_read_b128 v[178:181], v169 offset:2048
	ds_read_b128 v[182:185], v169 offset:3072
	v_add_u32_e32 v169, s58, v148
	ds_read_b128 v[186:189], v169
	ds_read_b128 v[190:193], v169 offset:1024
	ds_read_b128 v[196:199], v169 offset:2048
	ds_read_b128 v[202:205], v169 offset:3072
	s_add_u32 s40, s52, 0x2b0000
	s_addc_u32 s41, s53, 0
	s_mov_b32 m0, s25
	ds_read_b128 v[206:209], v168 offset:32768
	ds_read_b128 v[210:213], v168 offset:33792
	ds_read_b128 v[214:217], v168 offset:34816
	ds_read_b128 v[218:221], v168 offset:35840
	ds_read_b128 v[222:225], v168 offset:36864
	ds_read_b128 v[226:229], v168 offset:37888
	ds_read_b128 v[230:233], v168 offset:38912
	ds_read_b128 v[234:237], v168 offset:39936
	global_load_lds_dwordx4 v130, s[40:41]
	s_mov_b32 m0, s26
	s_nop 0
	global_load_lds_dwordx4 v134, s[40:41]
	s_waitcnt vmcnt(8)
	s_waitcnt lgkmcnt(0)
	s_setprio 1
	s_barrier
; #define PG8_STAGE(bufoff, gbase, voff) do { _Pragma("unroll") for (int _i = 0; _i < 2; ++_i) \
;         __builtin_amdgcn_global_load_lds((const unsigned*)((const char*)(gbase) + (voff)[_i]), (PG8_LAS unsigned*)(lds + (bufoff) + ldsw + _i * 8192), 16, 0, 0); } while (0)
; #define PG8_LDA(dst, b, h) do { _Pragma("unroll") for (int m = 0; m < 4; ++m) _Pragma("unroll") for (int k = 0; k < 2; ++k) dst[m][k] = *(const PG8_LAS bf16x8*)(lds + PG8_SA(b, h) + aoff + m * 2048 + k * 1024); } while (0)
; #define PG8_MMA(ai, bj, At, Bt) do { __builtin_amdgcn_s_setprio(1); _Pragma("unroll") for (int m = 0; m < 4; ++m) _Pragma("unroll") for (int n = 0; n < 2; ++n) _Pragma("unroll") for (int k = 0; k < 2; ++k) \
;         acc[ai][bj][m][n] = __builtin_amdgcn_mfma_f32_16x16x32_bf16(Bt[n][k], At[m][k], acc[ai][bj][m][n], 0, 0, 0); __builtin_amdgcn_s_setprio(0); } while (0)
; #define PG8_WAIT_V(n) asm volatile("s_waitcnt vmcnt(" #n ")" ::: "memory")
; #define PG8_WAIT_L(n) asm volatile("s_waitcnt lgkmcnt(" #n ")" ::: "memory")
; #define PG8_BAR __builtin_amdgcn_s_barrier()
; #define PG8_SCHED __builtin_amdgcn_sched_barrier(0)
; template <class Epi, class Sched, bool ALIGN_EPI = false, bool SP2 = false>
; __device__ __forceinline__ void gemm_phase(PG8_LAS unsigned char* lds, const Gemm g, const Sched& S, const Epi& E) {
;     ...
;         for (int t = 0; t < nt; t += 2) {
;     ...
;             PG8_WAIT_V(8); PG8_WAIT_L(0); PG8_BAR; PG8_MMA(0, 0, At, B0); PG8_MMA(0, 1, At, B1); PG8_BAR; PG8_SCHED;
;             PG8_LDA(At, 1, 1); PG8_STAGE(PG8_SB(1, 0), b3, voffB); PG8_STAGE(PG8_SB(1, 1), b3 + hstep, voffB); PG8_STAGE(PG8_SA(1, 0), a3, voffA);
;             PG8_WAIT_V(8); PG8_WAIT_L(0); PG8_BAR; PG8_MMA(1, 0, At, B0); PG8_MMA(1, 1, At, B1); PG8_BAR; PG8_SCHED;
	v_mfma_f32_16x16x32_bf16 v[126:129], v[170:173], v[206:209], v[126:129]
	v_mfma_f32_16x16x32_bf16 v[126:129], v[174:177], v[210:213], v[126:129]
	v_mfma_f32_16x16x32_bf16 v[110:113], v[174:177], v[218:221], v[110:113]
	v_mfma_f32_16x16x32_bf16 v[110:113], v[170:173], v[214:217], v[110:113]
	v_mfma_f32_16x16x32_bf16 v[94:97], v[170:173], v[222:225], v[94:97]
	v_mfma_f32_16x16x32_bf16 v[94:97], v[174:177], v[226:229], v[94:97]
	v_mfma_f32_16x16x32_bf16 v[78:81], v[174:177], v[234:237], v[78:81]
	v_mfma_f32_16x16x32_bf16 v[78:81], v[170:173], v[230:233], v[78:81]
	v_mfma_f32_16x16x32_bf16 v[74:77], v[178:181], v[230:233], v[74:77]
	v_mfma_f32_16x16x32_bf16 v[74:77], v[182:185], v[234:237], v[74:77]
	v_mfma_f32_16x16x32_bf16 v[122:125], v[182:185], v[210:213], v[122:125]
	v_mfma_f32_16x16x32_bf16 v[122:125], v[178:181], v[206:209], v[122:125]
	v_mfma_f32_16x16x32_bf16 v[106:109], v[178:181], v[214:217], v[106:109]
	v_mfma_f32_16x16x32_bf16 v[106:109], v[182:185], v[218:221], v[106:109]
	v_mfma_f32_16x16x32_bf16 v[90:93], v[182:185], v[226:229], v[90:93]
	v_mfma_f32_16x16x32_bf16 v[90:93], v[178:181], v[222:225], v[90:93]
	s_setprio 0
	s_setprio 1
	v_mfma_f32_16x16x32_bf16 v[86:89], v[186:189], v[222:225], v[86:89]
	v_mfma_f32_16x16x32_bf16 v[86:89], v[190:193], v[226:229], v[86:89]
	v_mfma_f32_16x16x32_bf16 v[118:121], v[190:193], v[210:213], v[118:121]
	v_mfma_f32_16x16x32_bf16 v[118:121], v[186:189], v[206:209], v[118:121]
	v_mfma_f32_16x16x32_bf16 v[102:105], v[186:189], v[214:217], v[102:105]
	v_mfma_f32_16x16x32_bf16 v[102:105], v[190:193], v[218:221], v[102:105]
	v_mfma_f32_16x16x32_bf16 v[70:73], v[190:193], v[234:237], v[70:73]
	v_mfma_f32_16x16x32_bf16 v[70:73], v[186:189], v[230:233], v[70:73]
	v_mfma_f32_16x16x32_bf16 v[66:69], v[196:199], v[230:233], v[66:69]
	v_mfma_f32_16x16x32_bf16 v[66:69], v[202:205], v[234:237], v[66:69]
	v_mfma_f32_16x16x32_bf16 v[114:117], v[202:205], v[210:213], v[114:117]
	v_mfma_f32_16x16x32_bf16 v[114:117], v[196:199], v[206:209], v[114:117]
	v_mfma_f32_16x16x32_bf16 v[98:101], v[196:199], v[214:217], v[98:101]
	v_mfma_f32_16x16x32_bf16 v[98:101], v[202:205], v[218:221], v[98:101]
	v_mfma_f32_16x16x32_bf16 v[82:85], v[202:205], v[226:229], v[82:85]
	v_mfma_f32_16x16x32_bf16 v[82:85], v[196:199], v[222:225], v[82:85]
	s_barrier
	s_setprio 0
	s_add_i32 s40, s57, s3
	s_add_u32 s98, s50, s10
	s_addc_u32 s99, s51, s11
	s_mov_b32 m0, s40
	ds_read_b128 v[206:209], v168 offset:49152
	ds_read_b128 v[210:213], v168 offset:50176
	ds_read_b128 v[214:217], v168 offset:51200
	ds_read_b128 v[218:221], v168 offset:52224
	ds_read_b128 v[222:225], v168 offset:53248
	ds_read_b128 v[226:229], v168 offset:54272
	ds_read_b128 v[230:233], v168 offset:55296
	ds_read_b128 v[234:237], v168 offset:56320
	global_load_lds_dwordx4 v132, s[98:99]
	s_add_i32 m0, s40, 0x2000
	s_add_u32 s40, s50, 0x2b0080
	s_addc_u32 s41, s51, 0
	s_add_i32 s50, s58, s3
	global_load_lds_dwordx4 v136, s[98:99]
	s_mov_b32 m0, s50
	s_nop 0
	global_load_lds_dwordx4 v132, s[40:41]
	s_add_i32 m0, s50, 0x2000
	s_nop 0
	global_load_lds_dwordx4 v136, s[40:41]
	s_add_u32 s100, s52, s10
	s_addc_u32 s101, s53, s11
	s_mov_b32 m0, s28
	s_nop 0
	global_load_lds_dwordx4 v130, s[100:101]
	s_mov_b32 m0, s29
	s_nop 0
	global_load_lds_dwordx4 v134, s[100:101]
	s_waitcnt vmcnt(8)
	s_waitcnt lgkmcnt(0)
	s_setprio 1
	s_barrier
	v_mfma_f32_16x16x32_bf16 v[62:65], v[170:173], v[206:209], v[62:65]
	v_mfma_f32_16x16x32_bf16 v[62:65], v[174:177], v[210:213], v[62:65]
	v_mfma_f32_16x16x32_bf16 v[46:49], v[174:177], v[218:221], v[46:49]
	v_mfma_f32_16x16x32_bf16 v[46:49], v[170:173], v[214:217], v[46:49]
	v_mfma_f32_16x16x32_bf16 v[30:33], v[170:173], v[222:225], v[30:33]
	v_mfma_f32_16x16x32_bf16 v[30:33], v[174:177], v[226:229], v[30:33]
	v_mfma_f32_16x16x32_bf16 v[14:17], v[174:177], v[234:237], v[14:17]
	v_mfma_f32_16x16x32_bf16 v[14:17], v[170:173], v[230:233], v[14:17]
	v_mfma_f32_16x16x32_bf16 v[10:13], v[178:181], v[230:233], v[10:13]
	v_mfma_f32_16x16x32_bf16 v[10:13], v[182:185], v[234:237], v[10:13]
	v_mfma_f32_16x16x32_bf16 v[58:61], v[182:185], v[210:213], v[58:61]
	v_mfma_f32_16x16x32_bf16 v[58:61], v[178:181], v[206:209], v[58:61]
	v_mfma_f32_16x16x32_bf16 v[42:45], v[178:181], v[214:217], v[42:45]
	v_mfma_f32_16x16x32_bf16 v[42:45], v[182:185], v[218:221], v[42:45]
	v_mfma_f32_16x16x32_bf16 v[26:29], v[182:185], v[226:229], v[26:29]
	v_mfma_f32_16x16x32_bf16 v[26:29], v[178:181], v[222:225], v[26:29]
	s_setprio 0
	s_setprio 1
	v_mfma_f32_16x16x32_bf16 v[22:25], v[186:189], v[222:225], v[22:25]
	v_mfma_f32_16x16x32_bf16 v[22:25], v[190:193], v[226:229], v[22:25]
	v_mfma_f32_16x16x32_bf16 v[54:57], v[190:193], v[210:213], v[54:57]
	v_mfma_f32_16x16x32_bf16 v[54:57], v[186:189], v[206:209], v[54:57]
	v_mfma_f32_16x16x32_bf16 v[38:41], v[186:189], v[214:217], v[38:41]
	v_mfma_f32_16x16x32_bf16 v[38:41], v[190:193], v[218:221], v[38:41]
	v_mfma_f32_16x16x32_bf16 v[6:9], v[190:193], v[234:237], v[6:9]
	v_mfma_f32_16x16x32_bf16 v[6:9], v[186:189], v[230:233], v[6:9]
	v_mfma_f32_16x16x32_bf16 v[2:5], v[196:199], v[230:233], v[2:5]
	v_mfma_f32_16x16x32_bf16 v[2:5], v[202:205], v[234:237], v[2:5]
	v_mfma_f32_16x16x32_bf16 v[50:53], v[202:205], v[210:213], v[50:53]
	v_mfma_f32_16x16x32_bf16 v[50:53], v[196:199], v[206:209], v[50:53]
	v_mfma_f32_16x16x32_bf16 v[34:37], v[196:199], v[214:217], v[34:37]
	v_mfma_f32_16x16x32_bf16 v[34:37], v[202:205], v[218:221], v[34:37]
	v_mfma_f32_16x16x32_bf16 v[18:21], v[202:205], v[226:229], v[18:21]
	v_mfma_f32_16x16x32_bf16 v[18:21], v[196:199], v[222:225], v[18:21]
	s_barrier
	s_setprio 0
	s_add_i32 s56, s56, 2
	s_add_u32 s54, s54, 0x100
	s_addc_u32 s55, s55, 0
	s_cmpk_gt_u32 s56, 0xa9
	s_mov_b64 s[40:41], s[48:49]
	s_cbranch_scc0 .LBB0_1731
	s_and_b64 vcc, exec, s[12:13]
	s_cbranch_vccz .LBB0_1734
	s_barrier

; #define PG8_STAGE(bufoff, gbase, voff) do { _Pragma("unroll") for (int _i = 0; _i < 2; ++_i) \
;         __builtin_amdgcn_global_load_lds((const unsigned*)((const char*)(gbase) + (voff)[_i]), (PG8_LAS unsigned*)(lds + (bufoff) + ldsw + _i * 8192), 16, 0, 0); } while (0)
; #define PG8_WAIT_V(n) asm volatile("s_waitcnt vmcnt(" #n ")" ::: "memory")
; #define PG8_BAR __builtin_amdgcn_s_barrier()
;     __device__ __forceinline__ bool next(int i, Unit& u) const { if (!pg8::StaticOrder::next(i, u)) return false; if (u.pn >= 32) u.pn += 1; return true; }
;     __device__ __forceinline__ bool next(int i, Unit& u) const { if (i > 0 || c >= 204) return false; u.pm = c % 68; u.pn = 32; return true; }
;     __device__ __forceinline__ bool next(int i, Unit& u) const { if (i > 0) return false; u.pm = 64 + ((c & 63) >> 4); u.pn = c & 15; return true; }
; template <class Epi, class Sched, bool ALIGN_EPI = false, bool SP2 = false>
; __device__ __forceinline__ void gemm_phase(PG8_LAS unsigned char* lds, const Gemm g, const Sched& S, const Epi& E) {
;     ...
;     const int aoff = lds_byte(wr * 64 + fr, fq * 8), boff = lds_byte(wc * 32 + fr, fq * 8);
;     ...
;     Unit cur, nxt; int ui = 0;
;     if (!S.next(0, cur)) return;
;     f32x4 acc[2][2][4][2];
; #pragma unroll
;     for (int a = 0; a < 2; ++a)
; #pragma unroll
;         for (int b = 0; b < 2; ++b)
; #pragma unroll
;             for (int m = 0; m < 4; ++m)
; #pragma unroll
;                 for (int n = 0; n < 2; ++n) acc[a][b][m][n] = (f32x4){0.f, 0.f, 0.f, 0.f};
;     bf16x8 At[4][2], B0[2][2], B1[2][2];
;     const char* cA = (const char*)g.A + (size_t)cur.pm * tstep; const char* cB = (const char*)g.Bt + (size_t)cur.pn * tstep;
;     S.a_ready(cur);
;     if constexpr (SP2) {
;         PG8_STAGE(PG8_SB(0, 0), cB, voffB); PG8_STAGE(PG8_SB(0, 1), cB + hstep, voffB); PG8_STAGE(PG8_SA(0, 0), cA, voffA); PG8_STAGE(PG8_SA(0, 1), cA + hstep, voffA);
;         if (wr == 1) PG8_BAR;
;         PG8_WAIT_V(2); PG8_BAR;
;         PG8_STAGE(PG8_SB(1, 0), cB + kstep, voffB); PG8_STAGE(PG8_SA(1, 0), cA + kstep, voffA); PG8_STAGE(PG8_SB(1, 1), cB + hstep + kstep, voffB);
;         PG8_WAIT_V(6); PG8_BAR;
.LBB0_1745:
	v_bfe_u32 v132, v0, 4, 2
	s_lshl_b32 s12, s12, 5
	v_and_b32_e32 v133, 15, v0
	v_lshlrev_b32_e32 v1, 4, v132
	s_and_b32 s33, s12, 0x60
	v_lshlrev_b32_e32 v0, 2, v0
	v_lshl_or_b32 v1, v133, 6, v1
	s_lshl_b32 s12, s33, 7
	v_and_b32_e32 v0, 32, v0
	s_lshl_b32 s29, s10, 6
	v_bitop3_b32 v10, v1, s12, v0 bitop3:0xde
	s_lshl_b32 s10, s10, 13
	s_mov_b64 s[12:13], 0x80
	v_bitop3_b32 v11, v1, s10, v0 bitop3:0xde
	s_add_i32 m0, s26, 0x18000
	v_lshl_add_u64 v[0:1], v[8:9], 0, s[12:13]
	s_waitcnt vmcnt(2)
	s_barrier
	global_load_lds_dwordx4 v[0:1], off
	v_lshl_add_u64 v[0:1], v[6:7], 0, s[12:13]
	s_add_i32 m0, s26, 0x1a000
	s_add_i32 s34, s26, 0x8000
	s_add_i32 s35, s26, 0xa000
	global_load_lds_dwordx4 v[0:1], off
	v_lshl_add_u64 v[0:1], v[4:5], 0, s[12:13]
	s_mov_b32 m0, s34
	s_add_u32 s38, s2, 0x2b0080
	global_load_lds_dwordx4 v[0:1], off
	v_lshl_add_u64 v[0:1], v[2:3], 0, s[12:13]
	s_mov_b32 m0, s35
	s_addc_u32 s39, s3, 0
	global_load_lds_dwordx4 v[0:1], off
	s_add_i32 m0, s26, 0x1c000
	v_lshl_add_u64 v[0:1], s[38:39], 0, v[128:129]
	global_load_lds_dwordx4 v[0:1], off
	v_lshl_add_u64 v[0:1], s[38:39], 0, v[130:131]
	s_add_i32 m0, s26, 0x1e000
	s_add_i32 s46, 0, 0x14000
	global_load_lds_dwordx4 v[0:1], off
	s_waitcnt vmcnt(6)
	s_add_i32 s48, 0, 0x18000
	s_add_i32 s50, 0, 0x1c000
	v_add_u32_e32 v134, s31, v10
	v_add_u32_e32 v135, s46, v10
	s_add_i32 s31, s31, s36
	s_add_i32 s46, s46, s36
	v_add_u32_e32 v137, s48, v10
	v_add_u32_e32 v138, s50, v10
	s_add_i32 s48, s48, s36
	s_add_i32 s50, s50, s36
	s_add_i32 s42, s5, -2
	v_add_u32_e32 v136, 0, v11
	s_add_i32 s43, s26, 0xc000
	s_add_i32 s44, s26, 0xe000
	s_add_i32 s45, s31, 0x2000
	s_add_i32 s47, s46, 0x2000
	s_add_i32 s49, s48, 0x2000
	s_add_i32 s51, s50, 0x2000
	s_mov_b32 s38, 0
	v_mov_b64_e32 v[0:1], 0
	v_mov_b64_e32 v[2:3], 0
	v_mov_b64_e32 v[4:5], 0
	v_mov_b64_e32 v[6:7], 0
	v_mov_b64_e32 v[8:9], 0
	v_mov_b64_e32 v[10:11], 0
	v_mov_b64_e32 v[12:13], 0
	v_mov_b64_e32 v[14:15], 0
	v_mov_b64_e32 v[16:17], 0
	v_mov_b64_e32 v[18:19], 0
	v_mov_b64_e32 v[20:21], 0
	v_mov_b64_e32 v[22:23], 0
	v_mov_b64_e32 v[24:25], 0
	v_mov_b64_e32 v[26:27], 0
	v_mov_b64_e32 v[28:29], 0
	v_mov_b64_e32 v[30:31], 0
	v_mov_b64_e32 v[32:33], 0
	v_mov_b64_e32 v[34:35], 0
	v_mov_b64_e32 v[36:37], 0
	v_mov_b64_e32 v[38:39], 0
	v_mov_b64_e32 v[40:41], 0
	v_mov_b64_e32 v[42:43], 0
	v_mov_b64_e32 v[44:45], 0
	v_mov_b64_e32 v[46:47], 0
	v_mov_b64_e32 v[48:49], 0
	v_mov_b64_e32 v[50:51], 0
	v_mov_b64_e32 v[52:53], 0
	v_mov_b64_e32 v[54:55], 0
	v_mov_b64_e32 v[56:57], 0
	v_mov_b64_e32 v[58:59], 0
	v_mov_b64_e32 v[60:61], 0
	v_mov_b64_e32 v[62:63], 0
	v_mov_b64_e32 v[64:65], 0
	v_mov_b64_e32 v[66:67], 0
	v_mov_b64_e32 v[68:69], 0
	v_mov_b64_e32 v[70:71], 0
	v_mov_b64_e32 v[72:73], 0
	v_mov_b64_e32 v[74:75], 0
	v_mov_b64_e32 v[76:77], 0
	v_mov_b64_e32 v[78:79], 0
	v_mov_b64_e32 v[80:81], 0
	v_mov_b64_e32 v[82:83], 0
	v_mov_b64_e32 v[84:85], 0
	v_mov_b64_e32 v[86:87], 0
	v_mov_b64_e32 v[88:89], 0
	v_mov_b64_e32 v[90:91], 0
	v_mov_b64_e32 v[92:93], 0
	v_mov_b64_e32 v[94:95], 0
	v_mov_b64_e32 v[96:97], 0
	v_mov_b64_e32 v[98:99], 0
	v_mov_b64_e32 v[100:101], 0
	v_mov_b64_e32 v[102:103], 0
	v_mov_b64_e32 v[104:105], 0
	v_mov_b64_e32 v[106:107], 0
	v_mov_b64_e32 v[108:109], 0
	v_mov_b64_e32 v[110:111], 0
	v_mov_b64_e32 v[112:113], 0
	v_mov_b64_e32 v[114:115], 0
	v_mov_b64_e32 v[116:117], 0
	v_mov_b64_e32 v[118:119], 0
	v_mov_b64_e32 v[120:121], 0
	v_mov_b64_e32 v[122:123], 0
	v_mov_b64_e32 v[124:125], 0
	v_mov_b64_e32 v[126:127], 0
	v_mov_b32_e32 v129, 0
	s_barrier
